# GEMM K-loops: snake-order MFMAs within each 8-group so consecutive MFMAs share one operand (same accumulate chains)
# baseline (speedup 1.0000x reference)
; #define PG8_STAGE(bufoff, gbase, voff) do { _Pragma("unroll") for (int _i = 0; _i < 2; ++_i) \
;         __builtin_amdgcn_global_load_lds((const unsigned*)((const char*)(gbase) + (voff)[_i]), (PG8_LAS unsigned*)(lds + (bufoff) + ldsw + _i * 8192), 16, 0, 0); } while (0)
; #define PG8_LDA(dst, b, h) do { _Pragma("unroll") for (int m = 0; m < 4; ++m) _Pragma("unroll") for (int k = 0; k < 2; ++k) dst[m][k] = *(const PG8_LAS bf16x8*)(lds + PG8_SA(b, h) + aoff + m * 2048 + k * 1024); } while (0)
; #define PG8_LDB(dst, b, h) do { _Pragma("unroll") for (int n = 0; n < 2; ++n) _Pragma("unroll") for (int k = 0; k < 2; ++k) dst[n][k] = *(const PG8_LAS bf16x8*)(lds + PG8_SB(b, h) + boff + n * 2048 + k * 1024); } while (0)
; #define PG8_MMA(ai, bj, At, Bt) do { __builtin_amdgcn_s_setprio(1); _Pragma("unroll") for (int m = 0; m < 4; ++m) _Pragma("unroll") for (int n = 0; n < 2; ++n) _Pragma("unroll") for (int k = 0; k < 2; ++k) \
;         acc[ai][bj][m][n] = __builtin_amdgcn_mfma_f32_16x16x32_bf16(Bt[n][k], At[m][k], acc[ai][bj][m][n], 0, 0, 0); __builtin_amdgcn_s_setprio(0); } while (0)
; #define PG8_WAIT_V(n) asm volatile("s_waitcnt vmcnt(" #n ")" ::: "memory")
; #define PG8_WAIT_L(n) asm volatile("s_waitcnt lgkmcnt(" #n ")" ::: "memory")
; #define PG8_BAR __builtin_amdgcn_s_barrier()
; #define PG8_SCHED __builtin_amdgcn_sched_barrier(0)
; template <class Epi, class Sched, bool ALIGN_EPI = false, bool SP2 = false>
; __device__ __forceinline__ void gemm_phase(PG8_LAS unsigned char* lds, const Gemm g, const Sched& S, const Epi& E) {
;     ...
;         for (int t = 0; t < nt; t += 2) {
;             const bool last = (t == nt - 2);
;             const char* a1 = cA + (size_t)(t + 1) * kstep;
;             const char* a2 = last ? nA : cA + (size_t)(t + 2) * kstep; const char* b2 = last ? nB : cB + (size_t)(t + 2) * kstep;
;             const char* a3 = a2 + kstep; const char* b3 = b2 + kstep;
;             if (last && has_next) S.a_ready(nxt);
;             if constexpr (SP2) {
;             PG8_LDB(B0, 0, 0); PG8_LDB(B1, 0, 1); PG8_SCHED; PG8_LDA(At, 0, 0); PG8_STAGE(PG8_SA(1, 1), a1 + hstep, voffA);
;             PG8_WAIT_V(8); PG8_WAIT_L(0); PG8_BAR; PG8_MMA(0, 0, At, B0); PG8_MMA(0, 1, At, B1); PG8_BAR; PG8_SCHED;
;             PG8_LDA(At, 0, 1); PG8_STAGE(PG8_SB(0, 0), b2, voffB); PG8_STAGE(PG8_SB(0, 1), b2 + hstep, voffB); PG8_STAGE(PG8_SA(0, 0), a2, voffA);
.LBB0_265:
	s_add_u32 s10, s16, 0xfff80080
	s_addc_u32 s11, s17, -1
	s_add_i32 s27, 0, 0x10000
	s_cmp_eq_u32 s23, 28
	s_cselect_b32 s51, s5, s11
	s_cselect_b32 s50, s7, s10
	s_cselect_b32 s19, s8, s22
	s_cselect_b32 s18, s9, s15
	s_add_i32 s10, 0, 0x14000
	v_add_u32_e32 v168, s27, v157
	v_add_u32_e32 v184, s10, v157
	ds_read_b128 v[152:155], v168
	ds_read_b128 v[160:163], v168 offset:1024
	ds_read_b128 v[164:167], v168 offset:2048
	ds_read_b128 v[168:171], v168 offset:3072
	ds_read_b128 v[172:175], v184
	ds_read_b128 v[176:179], v184 offset:1024
	ds_read_b128 v[180:183], v184 offset:2048
	ds_read_b128 v[184:187], v184 offset:3072
	v_lshl_add_u64 v[200:201], s[16:17], 0, v[148:149]
	s_add_i32 m0, s57, 0xc000
	ds_read_b128 v[188:191], v159
	ds_read_b128 v[192:195], v159 offset:1024
	ds_read_b128 v[196:199], v159 offset:2048
	ds_read_b128 v[216:219], v159 offset:3072
	ds_read_b128 v[220:223], v159 offset:4096
	ds_read_b128 v[224:227], v159 offset:5120
	ds_read_b128 v[228:231], v159 offset:6144
	ds_read_b128 v[232:235], v159 offset:7168
	global_load_lds_dwordx4 v[200:201], off
	v_lshl_add_u64 v[200:201], s[16:17], 0, v[150:151]
	s_add_i32 m0, s57, 0xe000
	s_nop 0
	global_load_lds_dwordx4 v[200:201], off
	s_waitcnt vmcnt(8)
	s_waitcnt lgkmcnt(0)
	s_barrier
	s_setprio 1
	s_waitcnt lgkmcnt(0)
	v_mfma_f32_16x16x32_bf16 v[126:129], v[152:155], v[188:191], v[126:129]
	v_mfma_f32_16x16x32_bf16 v[122:125], v[164:167], v[188:191], v[122:125]
	v_mfma_f32_16x16x32_bf16 v[106:109], v[164:167], v[196:199], v[106:109]
	v_mfma_f32_16x16x32_bf16 v[110:113], v[152:155], v[196:199], v[110:113]
	v_mfma_f32_16x16x32_bf16 v[94:97], v[152:155], v[220:223], v[94:97]
	v_mfma_f32_16x16x32_bf16 v[90:93], v[164:167], v[220:223], v[90:93]
	v_mfma_f32_16x16x32_bf16 v[74:77], v[164:167], v[228:231], v[74:77]
	v_mfma_f32_16x16x32_bf16 v[78:81], v[152:155], v[228:231], v[78:81]
	v_mfma_f32_16x16x32_bf16 v[126:129], v[160:163], v[192:195], v[126:129]
	v_mfma_f32_16x16x32_bf16 v[122:125], v[168:171], v[192:195], v[122:125]
	v_mfma_f32_16x16x32_bf16 v[106:109], v[168:171], v[216:219], v[106:109]
	v_mfma_f32_16x16x32_bf16 v[110:113], v[160:163], v[216:219], v[110:113]
	v_mfma_f32_16x16x32_bf16 v[94:97], v[160:163], v[224:227], v[94:97]
	v_mfma_f32_16x16x32_bf16 v[90:93], v[168:171], v[224:227], v[90:93]
	v_mfma_f32_16x16x32_bf16 v[74:77], v[168:171], v[232:235], v[74:77]
	v_mfma_f32_16x16x32_bf16 v[78:81], v[160:163], v[232:235], v[78:81]
	s_setprio 0
	s_setprio 1
	v_mfma_f32_16x16x32_bf16 v[118:121], v[172:175], v[188:191], v[118:121]
	v_mfma_f32_16x16x32_bf16 v[114:117], v[180:183], v[188:191], v[114:117]
	v_mfma_f32_16x16x32_bf16 v[98:101], v[180:183], v[196:199], v[98:101]
	v_mfma_f32_16x16x32_bf16 v[102:105], v[172:175], v[196:199], v[102:105]
	v_mfma_f32_16x16x32_bf16 v[86:89], v[172:175], v[220:223], v[86:89]
	v_mfma_f32_16x16x32_bf16 v[82:85], v[180:183], v[220:223], v[82:85]
	v_mfma_f32_16x16x32_bf16 v[66:69], v[180:183], v[228:231], v[66:69]
	v_mfma_f32_16x16x32_bf16 v[70:73], v[172:175], v[228:231], v[70:73]
	v_mfma_f32_16x16x32_bf16 v[118:121], v[176:179], v[192:195], v[118:121]
	v_mfma_f32_16x16x32_bf16 v[114:117], v[184:187], v[192:195], v[114:117]
	v_mfma_f32_16x16x32_bf16 v[98:101], v[184:187], v[216:219], v[98:101]
	v_mfma_f32_16x16x32_bf16 v[102:105], v[176:179], v[216:219], v[102:105]
	v_mfma_f32_16x16x32_bf16 v[86:89], v[176:179], v[224:227], v[86:89]
	v_mfma_f32_16x16x32_bf16 v[82:85], v[184:187], v[224:227], v[82:85]
	v_mfma_f32_16x16x32_bf16 v[66:69], v[184:187], v[232:235], v[66:69]
	v_mfma_f32_16x16x32_bf16 v[70:73], v[176:179], v[232:235], v[70:73]
	s_setprio 0
	s_barrier
	s_add_i32 s11, s27, s56
	v_lshl_add_u64 v[200:201], s[18:19], 0, v[0:1]
	s_mov_b32 m0, s11
	ds_read_b128 v[188:191], v159 offset:16384
	ds_read_b128 v[192:195], v159 offset:17408
	ds_read_b128 v[196:199], v159 offset:18432
	ds_read_b128 v[216:219], v159 offset:19456
	ds_read_b128 v[220:223], v159 offset:20480
	ds_read_b128 v[224:227], v159 offset:21504
	ds_read_b128 v[228:231], v159 offset:22528
	ds_read_b128 v[232:235], v159 offset:23552
	global_load_lds_dwordx4 v[200:201], off
	s_add_i32 m0, s11, 0x2000
	s_add_u32 s38, s18, 0x80000
	v_lshl_add_u64 v[236:237], s[18:19], 0, v[142:143]
	s_addc_u32 s39, s19, 0
	s_add_i32 s10, s10, s56
	global_load_lds_dwordx4 v[236:237], off
	v_lshl_add_u64 v[238:239], s[38:39], 0, v[0:1]
	s_mov_b32 m0, s10
	v_lshl_add_u64 v[240:241], s[50:51], 0, v[144:145]
	global_load_lds_dwordx4 v[238:239], off
	v_lshl_add_u64 v[238:239], s[38:39], 0, v[142:143]
	s_add_i32 m0, s10, 0x2000
	s_nop 0
	global_load_lds_dwordx4 v[238:239], off
	v_lshl_add_u64 v[238:239], s[50:51], 0, v[146:147]
	s_mov_b32 m0, s57
	s_nop 0
	global_load_lds_dwordx4 v[238:239], off
	s_mov_b32 m0, s58
	s_nop 0
	global_load_lds_dwordx4 v[240:241], off
	s_waitcnt vmcnt(8)
	s_waitcnt lgkmcnt(0)
	s_barrier
; #define PG8_STAGE(bufoff, gbase, voff) do { _Pragma("unroll") for (int _i = 0; _i < 2; ++_i) \
;         __builtin_amdgcn_global_load_lds((const unsigned*)((const char*)(gbase) + (voff)[_i]), (PG8_LAS unsigned*)(lds + (bufoff) + ldsw + _i * 8192), 16, 0, 0); } while (0)
; #define PG8_LDA(dst, b, h) do { _Pragma("unroll") for (int m = 0; m < 4; ++m) _Pragma("unroll") for (int k = 0; k < 2; ++k) dst[m][k] = *(const PG8_LAS bf16x8*)(lds + PG8_SA(b, h) + aoff + m * 2048 + k * 1024); } while (0)
; #define PG8_LDB(dst, b, h) do { _Pragma("unroll") for (int n = 0; n < 2; ++n) _Pragma("unroll") for (int k = 0; k < 2; ++k) dst[n][k] = *(const PG8_LAS bf16x8*)(lds + PG8_SB(b, h) + boff + n * 2048 + k * 1024); } while (0)
; #define PG8_MMA(ai, bj, At, Bt) do { __builtin_amdgcn_s_setprio(1); _Pragma("unroll") for (int m = 0; m < 4; ++m) _Pragma("unroll") for (int n = 0; n < 2; ++n) _Pragma("unroll") for (int k = 0; k < 2; ++k) \
;         acc[ai][bj][m][n] = __builtin_amdgcn_mfma_f32_16x16x32_bf16(Bt[n][k], At[m][k], acc[ai][bj][m][n], 0, 0, 0); __builtin_amdgcn_s_setprio(0); } while (0)
; #define PG8_WAIT_V(n) asm volatile("s_waitcnt vmcnt(" #n ")" ::: "memory")
; #define PG8_WAIT_L(n) asm volatile("s_waitcnt lgkmcnt(" #n ")" ::: "memory")
; #define PG8_BAR __builtin_amdgcn_s_barrier()
; #define PG8_SCHED __builtin_amdgcn_sched_barrier(0)
; template <class Epi, class Sched, bool ALIGN_EPI = false, bool SP2 = false>
; __device__ __forceinline__ void gemm_phase(PG8_LAS unsigned char* lds, const Gemm g, const Sched& S, const Epi& E) {
;     ...
;             PG8_WAIT_V(8); PG8_WAIT_L(0); PG8_BAR; PG8_MMA(1, 0, At, B0); PG8_MMA(1, 1, At, B1); PG8_BAR; PG8_SCHED;
;             PG8_LDB(B0, 1, 0); PG8_LDB(B1, 1, 1); PG8_SCHED; PG8_LDA(At, 1, 0); PG8_STAGE(PG8_SA(0, 1), a2 + hstep, voffA);
;             PG8_WAIT_V(8); PG8_WAIT_L(0); PG8_BAR; PG8_MMA(0, 0, At, B0); PG8_MMA(0, 1, At, B1); PG8_BAR; PG8_SCHED;
	s_setprio 1
	s_waitcnt lgkmcnt(0)
	v_mfma_f32_16x16x32_bf16 v[62:65], v[152:155], v[188:191], v[62:65]
	v_mfma_f32_16x16x32_bf16 v[58:61], v[164:167], v[188:191], v[58:61]
	v_mfma_f32_16x16x32_bf16 v[42:45], v[164:167], v[196:199], v[42:45]
	v_mfma_f32_16x16x32_bf16 v[50:53], v[152:155], v[196:199], v[50:53]
	v_mfma_f32_16x16x32_bf16 v[34:37], v[152:155], v[220:223], v[34:37]
	v_mfma_f32_16x16x32_bf16 v[26:29], v[164:167], v[220:223], v[26:29]
	v_mfma_f32_16x16x32_bf16 v[10:13], v[164:167], v[228:231], v[10:13]
	v_mfma_f32_16x16x32_bf16 v[18:21], v[152:155], v[228:231], v[18:21]
	v_mfma_f32_16x16x32_bf16 v[62:65], v[160:163], v[192:195], v[62:65]
	v_mfma_f32_16x16x32_bf16 v[58:61], v[168:171], v[192:195], v[58:61]
	v_mfma_f32_16x16x32_bf16 v[42:45], v[168:171], v[216:219], v[42:45]
	v_mfma_f32_16x16x32_bf16 v[50:53], v[160:163], v[216:219], v[50:53]
	v_mfma_f32_16x16x32_bf16 v[34:37], v[160:163], v[224:227], v[34:37]
	v_mfma_f32_16x16x32_bf16 v[26:29], v[168:171], v[224:227], v[26:29]
	v_mfma_f32_16x16x32_bf16 v[10:13], v[168:171], v[232:235], v[10:13]
	v_mfma_f32_16x16x32_bf16 v[18:21], v[160:163], v[232:235], v[18:21]
	s_setprio 0
	s_setprio 1
	v_mfma_f32_16x16x32_bf16 v[54:57], v[172:175], v[188:191], v[54:57]
	v_mfma_f32_16x16x32_bf16 v[46:49], v[180:183], v[188:191], v[46:49]
	v_mfma_f32_16x16x32_bf16 v[30:33], v[180:183], v[196:199], v[30:33]
	v_mfma_f32_16x16x32_bf16 v[38:41], v[172:175], v[196:199], v[38:41]
	v_mfma_f32_16x16x32_bf16 v[22:25], v[172:175], v[220:223], v[22:25]
	v_mfma_f32_16x16x32_bf16 v[14:17], v[180:183], v[220:223], v[14:17]
	v_mfma_f32_16x16x32_bf16 v[2:5], v[180:183], v[228:231], v[2:5]
	v_mfma_f32_16x16x32_bf16 v[6:9], v[172:175], v[228:231], v[6:9]
	v_mfma_f32_16x16x32_bf16 v[54:57], v[176:179], v[192:195], v[54:57]
	v_mfma_f32_16x16x32_bf16 v[46:49], v[184:187], v[192:195], v[46:49]
	v_mfma_f32_16x16x32_bf16 v[30:33], v[184:187], v[216:219], v[30:33]
	v_mfma_f32_16x16x32_bf16 v[38:41], v[176:179], v[216:219], v[38:41]
	v_mfma_f32_16x16x32_bf16 v[22:25], v[176:179], v[224:227], v[22:25]
	v_mfma_f32_16x16x32_bf16 v[14:17], v[184:187], v[224:227], v[14:17]
	v_mfma_f32_16x16x32_bf16 v[2:5], v[184:187], v[232:235], v[2:5]
	v_mfma_f32_16x16x32_bf16 v[6:9], v[176:179], v[232:235], v[6:9]
	s_setprio 0
	s_barrier
	s_add_i32 s10, 0, 0x18000
	s_add_i32 s11, 0, 0x1c000
	v_add_u32_e32 v168, s10, v157
	v_add_u32_e32 v184, s11, v157
	ds_read_b128 v[152:155], v168
	ds_read_b128 v[160:163], v168 offset:1024
	ds_read_b128 v[164:167], v168 offset:2048
	ds_read_b128 v[168:171], v168 offset:3072
	ds_read_b128 v[172:175], v184
	ds_read_b128 v[176:179], v184 offset:1024
	ds_read_b128 v[180:183], v184 offset:2048
	ds_read_b128 v[184:187], v184 offset:3072
	s_add_u32 s38, s50, 0x80000
	s_addc_u32 s39, s51, 0
	s_mov_b32 m0, s59
	v_lshl_add_u64 v[242:243], s[38:39], 0, v[146:147]
	ds_read_b128 v[188:191], v159 offset:32768
	ds_read_b128 v[192:195], v159 offset:33792
	ds_read_b128 v[196:199], v159 offset:34816
	ds_read_b128 v[216:219], v159 offset:35840
	ds_read_b128 v[220:223], v159 offset:36864
	ds_read_b128 v[224:227], v159 offset:37888
	ds_read_b128 v[228:231], v159 offset:38912
	ds_read_b128 v[232:235], v159 offset:39936
	global_load_lds_dwordx4 v[242:243], off
	v_lshl_add_u64 v[242:243], s[38:39], 0, v[144:145]
	s_mov_b32 m0, s60
	s_nop 0
	global_load_lds_dwordx4 v[242:243], off
	s_waitcnt vmcnt(8)
	s_waitcnt lgkmcnt(0)
	s_barrier
	s_setprio 1
	s_waitcnt lgkmcnt(0)
	v_mfma_f32_16x16x32_bf16 v[126:129], v[152:155], v[188:191], v[126:129]
	v_mfma_f32_16x16x32_bf16 v[122:125], v[164:167], v[188:191], v[122:125]
	v_mfma_f32_16x16x32_bf16 v[106:109], v[164:167], v[196:199], v[106:109]
	v_mfma_f32_16x16x32_bf16 v[110:113], v[152:155], v[196:199], v[110:113]
	v_mfma_f32_16x16x32_bf16 v[94:97], v[152:155], v[220:223], v[94:97]
	v_mfma_f32_16x16x32_bf16 v[90:93], v[164:167], v[220:223], v[90:93]
	v_mfma_f32_16x16x32_bf16 v[74:77], v[164:167], v[228:231], v[74:77]
	v_mfma_f32_16x16x32_bf16 v[78:81], v[152:155], v[228:231], v[78:81]
	v_mfma_f32_16x16x32_bf16 v[126:129], v[160:163], v[192:195], v[126:129]
	v_mfma_f32_16x16x32_bf16 v[122:125], v[168:171], v[192:195], v[122:125]
	v_mfma_f32_16x16x32_bf16 v[106:109], v[168:171], v[216:219], v[106:109]
	v_mfma_f32_16x16x32_bf16 v[110:113], v[160:163], v[216:219], v[110:113]
	v_mfma_f32_16x16x32_bf16 v[94:97], v[160:163], v[224:227], v[94:97]
	v_mfma_f32_16x16x32_bf16 v[90:93], v[168:171], v[224:227], v[90:93]
	v_mfma_f32_16x16x32_bf16 v[74:77], v[168:171], v[232:235], v[74:77]
	v_mfma_f32_16x16x32_bf16 v[78:81], v[160:163], v[232:235], v[78:81]
	s_setprio 0
	s_setprio 1
	v_mfma_f32_16x16x32_bf16 v[118:121], v[172:175], v[188:191], v[118:121]
	v_mfma_f32_16x16x32_bf16 v[114:117], v[180:183], v[188:191], v[114:117]
	v_mfma_f32_16x16x32_bf16 v[98:101], v[180:183], v[196:199], v[98:101]
	v_mfma_f32_16x16x32_bf16 v[102:105], v[172:175], v[196:199], v[102:105]
	v_mfma_f32_16x16x32_bf16 v[86:89], v[172:175], v[220:223], v[86:89]
	v_mfma_f32_16x16x32_bf16 v[82:85], v[180:183], v[220:223], v[82:85]
	v_mfma_f32_16x16x32_bf16 v[66:69], v[180:183], v[228:231], v[66:69]
	v_mfma_f32_16x16x32_bf16 v[70:73], v[172:175], v[228:231], v[70:73]
	v_mfma_f32_16x16x32_bf16 v[118:121], v[176:179], v[192:195], v[118:121]
	v_mfma_f32_16x16x32_bf16 v[114:117], v[184:187], v[192:195], v[114:117]
	v_mfma_f32_16x16x32_bf16 v[98:101], v[184:187], v[216:219], v[98:101]
	v_mfma_f32_16x16x32_bf16 v[102:105], v[176:179], v[216:219], v[102:105]
	v_mfma_f32_16x16x32_bf16 v[86:89], v[176:179], v[224:227], v[86:89]
	v_mfma_f32_16x16x32_bf16 v[82:85], v[184:187], v[224:227], v[82:85]
	v_mfma_f32_16x16x32_bf16 v[66:69], v[184:187], v[232:235], v[66:69]
	v_mfma_f32_16x16x32_bf16 v[70:73], v[176:179], v[232:235], v[70:73]
	s_setprio 0
	s_barrier
; #define PG8_STAGE(bufoff, gbase, voff) do { _Pragma("unroll") for (int _i = 0; _i < 2; ++_i) \
;         __builtin_amdgcn_global_load_lds((const unsigned*)((const char*)(gbase) + (voff)[_i]), (PG8_LAS unsigned*)(lds + (bufoff) + ldsw + _i * 8192), 16, 0, 0); } while (0)
; #define PG8_LDA(dst, b, h) do { _Pragma("unroll") for (int m = 0; m < 4; ++m) _Pragma("unroll") for (int k = 0; k < 2; ++k) dst[m][k] = *(const PG8_LAS bf16x8*)(lds + PG8_SA(b, h) + aoff + m * 2048 + k * 1024); } while (0)
; #define PG8_MMA(ai, bj, At, Bt) do { __builtin_amdgcn_s_setprio(1); _Pragma("unroll") for (int m = 0; m < 4; ++m) _Pragma("unroll") for (int n = 0; n < 2; ++n) _Pragma("unroll") for (int k = 0; k < 2; ++k) \
;         acc[ai][bj][m][n] = __builtin_amdgcn_mfma_f32_16x16x32_bf16(Bt[n][k], At[m][k], acc[ai][bj][m][n], 0, 0, 0); __builtin_amdgcn_s_setprio(0); } while (0)
; #define PG8_WAIT_V(n) asm volatile("s_waitcnt vmcnt(" #n ")" ::: "memory")
; #define PG8_WAIT_L(n) asm volatile("s_waitcnt lgkmcnt(" #n ")" ::: "memory")
; #define PG8_BAR __builtin_amdgcn_s_barrier()
; #define PG8_SCHED __builtin_amdgcn_sched_barrier(0)
; template <class Epi, class Sched, bool ALIGN_EPI = false, bool SP2 = false>
; __device__ __forceinline__ void gemm_phase(PG8_LAS unsigned char* lds, const Gemm g, const Sched& S, const Epi& E) {
;     ...
;             PG8_LDA(At, 1, 1); PG8_STAGE(PG8_SB(1, 0), b3, voffB); PG8_STAGE(PG8_SB(1, 1), b3 + hstep, voffB); PG8_STAGE(PG8_SA(1, 0), a3, voffA);
;             PG8_WAIT_V(8); PG8_WAIT_L(0); PG8_BAR; PG8_MMA(1, 0, At, B0); PG8_MMA(1, 1, At, B1); PG8_BAR; PG8_SCHED;
	s_add_i32 s10, s10, s56
	v_lshl_add_u64 v[200:201], v[200:201], 0, s[30:31]
	s_mov_b32 m0, s10
	ds_read_b128 v[188:191], v159 offset:49152
	ds_read_b128 v[192:195], v159 offset:50176
	ds_read_b128 v[196:199], v159 offset:51200
	ds_read_b128 v[216:219], v159 offset:52224
	ds_read_b128 v[220:223], v159 offset:53248
	ds_read_b128 v[224:227], v159 offset:54272
	ds_read_b128 v[228:231], v159 offset:55296
	ds_read_b128 v[232:235], v159 offset:56320
	global_load_lds_dwordx4 v[200:201], off
	s_add_i32 m0, s10, 0x2000
	s_add_u32 s18, s18, 0x80080
	v_lshl_add_u64 v[200:201], v[236:237], 0, s[30:31]
	s_addc_u32 s19, s19, 0
	s_add_i32 s10, s11, s56
	global_load_lds_dwordx4 v[200:201], off
	v_lshl_add_u64 v[200:201], s[18:19], 0, v[0:1]
	s_mov_b32 m0, s10
	s_nop 0
	global_load_lds_dwordx4 v[200:201], off
	v_lshl_add_u64 v[200:201], s[18:19], 0, v[142:143]
	s_add_i32 m0, s10, 0x2000
	s_nop 0
	global_load_lds_dwordx4 v[200:201], off
	v_lshl_add_u64 v[200:201], v[238:239], 0, s[30:31]
	s_mov_b32 m0, s61
	s_nop 0
	global_load_lds_dwordx4 v[200:201], off
	v_lshl_add_u64 v[200:201], v[240:241], 0, s[30:31]
	s_mov_b32 m0, s62
	s_nop 0
	global_load_lds_dwordx4 v[200:201], off
	s_waitcnt vmcnt(8)
	s_waitcnt lgkmcnt(0)
	s_barrier
	s_setprio 1
	s_waitcnt lgkmcnt(0)
	v_mfma_f32_16x16x32_bf16 v[62:65], v[152:155], v[188:191], v[62:65]
	v_mfma_f32_16x16x32_bf16 v[58:61], v[164:167], v[188:191], v[58:61]
	v_mfma_f32_16x16x32_bf16 v[42:45], v[164:167], v[196:199], v[42:45]
	v_mfma_f32_16x16x32_bf16 v[50:53], v[152:155], v[196:199], v[50:53]
	v_mfma_f32_16x16x32_bf16 v[34:37], v[152:155], v[220:223], v[34:37]
	v_mfma_f32_16x16x32_bf16 v[26:29], v[164:167], v[220:223], v[26:29]
	v_mfma_f32_16x16x32_bf16 v[10:13], v[164:167], v[228:231], v[10:13]
	v_mfma_f32_16x16x32_bf16 v[18:21], v[152:155], v[228:231], v[18:21]
	v_mfma_f32_16x16x32_bf16 v[62:65], v[160:163], v[192:195], v[62:65]
	v_mfma_f32_16x16x32_bf16 v[58:61], v[168:171], v[192:195], v[58:61]
	v_mfma_f32_16x16x32_bf16 v[42:45], v[168:171], v[216:219], v[42:45]
	v_mfma_f32_16x16x32_bf16 v[50:53], v[160:163], v[216:219], v[50:53]
	v_mfma_f32_16x16x32_bf16 v[34:37], v[160:163], v[224:227], v[34:37]
	v_mfma_f32_16x16x32_bf16 v[26:29], v[168:171], v[224:227], v[26:29]
	v_mfma_f32_16x16x32_bf16 v[10:13], v[168:171], v[232:235], v[10:13]
	v_mfma_f32_16x16x32_bf16 v[18:21], v[160:163], v[232:235], v[18:21]
	s_setprio 0
	s_setprio 1
	v_mfma_f32_16x16x32_bf16 v[54:57], v[172:175], v[188:191], v[54:57]
	v_mfma_f32_16x16x32_bf16 v[46:49], v[180:183], v[188:191], v[46:49]
	v_mfma_f32_16x16x32_bf16 v[30:33], v[180:183], v[196:199], v[30:33]
	v_mfma_f32_16x16x32_bf16 v[38:41], v[172:175], v[196:199], v[38:41]
	v_mfma_f32_16x16x32_bf16 v[22:25], v[172:175], v[220:223], v[22:25]
	v_mfma_f32_16x16x32_bf16 v[14:17], v[180:183], v[220:223], v[14:17]
	v_mfma_f32_16x16x32_bf16 v[2:5], v[180:183], v[228:231], v[2:5]
	v_mfma_f32_16x16x32_bf16 v[6:9], v[172:175], v[228:231], v[6:9]
	v_mfma_f32_16x16x32_bf16 v[54:57], v[176:179], v[192:195], v[54:57]
	v_mfma_f32_16x16x32_bf16 v[46:49], v[184:187], v[192:195], v[46:49]
	v_mfma_f32_16x16x32_bf16 v[30:33], v[184:187], v[216:219], v[30:33]
	v_mfma_f32_16x16x32_bf16 v[38:41], v[176:179], v[216:219], v[38:41]
	v_mfma_f32_16x16x32_bf16 v[22:25], v[176:179], v[224:227], v[22:25]
	v_mfma_f32_16x16x32_bf16 v[14:17], v[184:187], v[224:227], v[14:17]
	v_mfma_f32_16x16x32_bf16 v[2:5], v[184:187], v[232:235], v[2:5]
	v_mfma_f32_16x16x32_bf16 v[6:9], v[176:179], v[232:235], v[6:9]
	s_setprio 0
	s_barrier
	s_add_i32 s23, s23, 2
	s_add_u32 s16, s16, 0x100
	s_addc_u32 s17, s17, 0
	s_add_u32 s15, s15, 0x100
	s_addc_u32 s22, s22, 0
	s_cmp_gt_u32 s23, 29
	s_cbranch_scc0 .LBB0_265
	s_and_b64 vcc, exec, s[24:25]
	s_cbranch_vccz .LBB0_268
	s_barrier

; #define PG8_STAGE(bufoff, gbase, voff) do { _Pragma("unroll") for (int _i = 0; _i < 2; ++_i) \
;         __builtin_amdgcn_global_load_lds((const unsigned*)((const char*)(gbase) + (voff)[_i]), (PG8_LAS unsigned*)(lds + (bufoff) + ldsw + _i * 8192), 16, 0, 0); } while (0)
; #define PG8_LDA(dst, b, h) do { _Pragma("unroll") for (int m = 0; m < 4; ++m) _Pragma("unroll") for (int k = 0; k < 2; ++k) dst[m][k] = *(const PG8_LAS bf16x8*)(lds + PG8_SA(b, h) + aoff + m * 2048 + k * 1024); } while (0)
; #define PG8_LDB(dst, b, h) do { _Pragma("unroll") for (int n = 0; n < 2; ++n) _Pragma("unroll") for (int k = 0; k < 2; ++k) dst[n][k] = *(const PG8_LAS bf16x8*)(lds + PG8_SB(b, h) + boff + n * 2048 + k * 1024); } while (0)
; #define PG8_MMA(ai, bj, At, Bt) do { __builtin_amdgcn_s_setprio(1); _Pragma("unroll") for (int m = 0; m < 4; ++m) _Pragma("unroll") for (int n = 0; n < 2; ++n) _Pragma("unroll") for (int k = 0; k < 2; ++k) \
;         acc[ai][bj][m][n] = __builtin_amdgcn_mfma_f32_16x16x32_bf16(Bt[n][k], At[m][k], acc[ai][bj][m][n], 0, 0, 0); __builtin_amdgcn_s_setprio(0); } while (0)
; #define PG8_WAIT_V(n) asm volatile("s_waitcnt vmcnt(" #n ")" ::: "memory")
; #define PG8_WAIT_L(n) asm volatile("s_waitcnt lgkmcnt(" #n ")" ::: "memory")
; #define PG8_BAR __builtin_amdgcn_s_barrier()
; #define PG8_SCHED __builtin_amdgcn_sched_barrier(0)
; template <class Epi, class Sched, bool ALIGN_EPI = false, bool SP2 = false>
; __device__ __forceinline__ void gemm_phase(PG8_LAS unsigned char* lds, const Gemm g, const Sched& S, const Epi& E) {
;     ...
;         for (int t = 0; t < nt; t += 2) {
;             const bool last = (t == nt - 2);
;             const char* a1 = cA + (size_t)(t + 1) * kstep;
;             const char* a2 = last ? nA : cA + (size_t)(t + 2) * kstep; const char* b2 = last ? nB : cB + (size_t)(t + 2) * kstep;
;             const char* a3 = a2 + kstep; const char* b3 = b2 + kstep;
;             if (last && has_next) S.a_ready(nxt);
;             if constexpr (SP2) {
;             PG8_LDB(B0, 0, 0); PG8_LDB(B1, 0, 1); PG8_SCHED; PG8_LDA(At, 0, 0); PG8_STAGE(PG8_SA(1, 1), a1 + hstep, voffA);
;             PG8_WAIT_V(8); PG8_WAIT_L(0); PG8_BAR; PG8_MMA(0, 0, At, B0); PG8_MMA(0, 1, At, B1); PG8_BAR; PG8_SCHED;
;             PG8_LDA(At, 0, 1); PG8_STAGE(PG8_SB(0, 0), b2, voffB); PG8_STAGE(PG8_SB(0, 1), b2 + hstep, voffB); PG8_STAGE(PG8_SA(0, 0), a2, voffA);
.LBB0_601:
	s_add_u32 s18, s16, 0x100
	s_addc_u32 s19, s17, 0
	s_add_i32 s10, 0, 0x10000
	s_cmp_eq_u32 s22, 28
	s_cselect_b32 s27, s5, s19
	s_cselect_b32 s26, s7, s18
	s_cselect_b32 s25, s8, s15
	s_cselect_b32 s24, s9, s14
	s_add_i32 s12, 0, 0x14000
	v_add_u32_e32 v160, s10, v187
	v_add_u32_e32 v176, s12, v187
	ds_read_b128 v[148:151], v160
	ds_read_b128 v[152:155], v160 offset:1024
	ds_read_b128 v[156:159], v160 offset:2048
	ds_read_b128 v[160:163], v160 offset:3072
	ds_read_b128 v[164:167], v176
	ds_read_b128 v[168:171], v176 offset:1024
	ds_read_b128 v[172:175], v176 offset:2048
	ds_read_b128 v[176:179], v176 offset:3072
	v_lshl_add_u64 v[184:185], s[16:17], 0, v[144:145]
	s_add_i32 m0, s61, 0xc000
	ds_read_b128 v[180:183], v189
	ds_read_b128 v[190:193], v189 offset:1024
	ds_read_b128 v[194:197], v189 offset:2048
	ds_read_b128 v[198:201], v189 offset:3072
	ds_read_b128 v[216:219], v189 offset:4096
	ds_read_b128 v[220:223], v189 offset:5120
	ds_read_b128 v[224:227], v189 offset:6144
	ds_read_b128 v[228:231], v189 offset:7168
	global_load_lds_dwordx4 v[184:185], off
	v_lshl_add_u64 v[184:185], s[16:17], 0, v[146:147]
	s_add_i32 m0, s61, 0xe000
	s_nop 0
	global_load_lds_dwordx4 v[184:185], off
	s_waitcnt vmcnt(8)
	s_waitcnt lgkmcnt(0)
	s_barrier
	s_setprio 1
	s_waitcnt lgkmcnt(0)
	v_mfma_f32_16x16x32_bf16 v[126:129], v[148:151], v[180:183], v[126:129]
	v_mfma_f32_16x16x32_bf16 v[122:125], v[156:159], v[180:183], v[122:125]
	v_mfma_f32_16x16x32_bf16 v[106:109], v[156:159], v[194:197], v[106:109]
	v_mfma_f32_16x16x32_bf16 v[110:113], v[148:151], v[194:197], v[110:113]
	v_mfma_f32_16x16x32_bf16 v[94:97], v[148:151], v[216:219], v[94:97]
	v_mfma_f32_16x16x32_bf16 v[90:93], v[156:159], v[216:219], v[90:93]
	v_mfma_f32_16x16x32_bf16 v[74:77], v[156:159], v[224:227], v[74:77]
	v_mfma_f32_16x16x32_bf16 v[78:81], v[148:151], v[224:227], v[78:81]
	v_mfma_f32_16x16x32_bf16 v[126:129], v[152:155], v[190:193], v[126:129]
	v_mfma_f32_16x16x32_bf16 v[122:125], v[160:163], v[190:193], v[122:125]
	v_mfma_f32_16x16x32_bf16 v[106:109], v[160:163], v[198:201], v[106:109]
	v_mfma_f32_16x16x32_bf16 v[110:113], v[152:155], v[198:201], v[110:113]
	v_mfma_f32_16x16x32_bf16 v[94:97], v[152:155], v[220:223], v[94:97]
	v_mfma_f32_16x16x32_bf16 v[90:93], v[160:163], v[220:223], v[90:93]
	v_mfma_f32_16x16x32_bf16 v[74:77], v[160:163], v[228:231], v[74:77]
	v_mfma_f32_16x16x32_bf16 v[78:81], v[152:155], v[228:231], v[78:81]
	s_setprio 0
	s_setprio 1
	v_mfma_f32_16x16x32_bf16 v[118:121], v[164:167], v[180:183], v[118:121]
	v_mfma_f32_16x16x32_bf16 v[114:117], v[172:175], v[180:183], v[114:117]
	v_mfma_f32_16x16x32_bf16 v[98:101], v[172:175], v[194:197], v[98:101]
	v_mfma_f32_16x16x32_bf16 v[102:105], v[164:167], v[194:197], v[102:105]
	v_mfma_f32_16x16x32_bf16 v[86:89], v[164:167], v[216:219], v[86:89]
	v_mfma_f32_16x16x32_bf16 v[82:85], v[172:175], v[216:219], v[82:85]
	v_mfma_f32_16x16x32_bf16 v[66:69], v[172:175], v[224:227], v[66:69]
	v_mfma_f32_16x16x32_bf16 v[70:73], v[164:167], v[224:227], v[70:73]
	v_mfma_f32_16x16x32_bf16 v[118:121], v[168:171], v[190:193], v[118:121]
	v_mfma_f32_16x16x32_bf16 v[114:117], v[176:179], v[190:193], v[114:117]
	v_mfma_f32_16x16x32_bf16 v[98:101], v[176:179], v[198:201], v[98:101]
	v_mfma_f32_16x16x32_bf16 v[102:105], v[168:171], v[198:201], v[102:105]
	v_mfma_f32_16x16x32_bf16 v[86:89], v[168:171], v[220:223], v[86:89]
	v_mfma_f32_16x16x32_bf16 v[82:85], v[176:179], v[220:223], v[82:85]
	v_mfma_f32_16x16x32_bf16 v[66:69], v[176:179], v[228:231], v[66:69]
	v_mfma_f32_16x16x32_bf16 v[70:73], v[168:171], v[228:231], v[70:73]
	s_setprio 0
	s_barrier
	s_add_i32 s10, s10, s60
	v_lshl_add_u64 v[184:185], s[24:25], 0, v[0:1]
	s_mov_b32 m0, s10
	ds_read_b128 v[180:183], v189 offset:16384
	ds_read_b128 v[190:193], v189 offset:17408
	ds_read_b128 v[194:197], v189 offset:18432
	ds_read_b128 v[198:201], v189 offset:19456
	ds_read_b128 v[216:219], v189 offset:20480
	ds_read_b128 v[220:223], v189 offset:21504
	ds_read_b128 v[224:227], v189 offset:22528
	ds_read_b128 v[228:231], v189 offset:23552
	global_load_lds_dwordx4 v[184:185], off
	s_add_i32 m0, s10, 0x2000
	s_add_u32 s10, s24, 0x80000
	v_lshl_add_u64 v[232:233], s[24:25], 0, v[142:143]
	s_addc_u32 s11, s25, 0
	s_add_i32 s12, s12, s60
	global_load_lds_dwordx4 v[232:233], off
	v_lshl_add_u64 v[234:235], s[10:11], 0, v[0:1]
	s_mov_b32 m0, s12
	v_lshl_add_u64 v[236:237], s[26:27], 0, v[142:143]
	global_load_lds_dwordx4 v[234:235], off
	v_lshl_add_u64 v[234:235], s[10:11], 0, v[142:143]
	s_add_i32 m0, s12, 0x2000
	s_nop 0
	global_load_lds_dwordx4 v[234:235], off
	v_lshl_add_u64 v[234:235], s[26:27], 0, v[0:1]
	s_mov_b32 m0, s61
	s_nop 0
	global_load_lds_dwordx4 v[234:235], off
	s_mov_b32 m0, s62
	s_nop 0
	global_load_lds_dwordx4 v[236:237], off
	s_waitcnt vmcnt(8)
	s_waitcnt lgkmcnt(0)
	s_barrier
; #define PG8_STAGE(bufoff, gbase, voff) do { _Pragma("unroll") for (int _i = 0; _i < 2; ++_i) \
;         __builtin_amdgcn_global_load_lds((const unsigned*)((const char*)(gbase) + (voff)[_i]), (PG8_LAS unsigned*)(lds + (bufoff) + ldsw + _i * 8192), 16, 0, 0); } while (0)
; #define PG8_LDA(dst, b, h) do { _Pragma("unroll") for (int m = 0; m < 4; ++m) _Pragma("unroll") for (int k = 0; k < 2; ++k) dst[m][k] = *(const PG8_LAS bf16x8*)(lds + PG8_SA(b, h) + aoff + m * 2048 + k * 1024); } while (0)
; #define PG8_LDB(dst, b, h) do { _Pragma("unroll") for (int n = 0; n < 2; ++n) _Pragma("unroll") for (int k = 0; k < 2; ++k) dst[n][k] = *(const PG8_LAS bf16x8*)(lds + PG8_SB(b, h) + boff + n * 2048 + k * 1024); } while (0)
; #define PG8_MMA(ai, bj, At, Bt) do { __builtin_amdgcn_s_setprio(1); _Pragma("unroll") for (int m = 0; m < 4; ++m) _Pragma("unroll") for (int n = 0; n < 2; ++n) _Pragma("unroll") for (int k = 0; k < 2; ++k) \
;         acc[ai][bj][m][n] = __builtin_amdgcn_mfma_f32_16x16x32_bf16(Bt[n][k], At[m][k], acc[ai][bj][m][n], 0, 0, 0); __builtin_amdgcn_s_setprio(0); } while (0)
; #define PG8_WAIT_V(n) asm volatile("s_waitcnt vmcnt(" #n ")" ::: "memory")
; #define PG8_WAIT_L(n) asm volatile("s_waitcnt lgkmcnt(" #n ")" ::: "memory")
; #define PG8_BAR __builtin_amdgcn_s_barrier()
; #define PG8_SCHED __builtin_amdgcn_sched_barrier(0)
; template <class Epi, class Sched, bool ALIGN_EPI = false, bool SP2 = false>
; __device__ __forceinline__ void gemm_phase(PG8_LAS unsigned char* lds, const Gemm g, const Sched& S, const Epi& E) {
;     ...
;             PG8_WAIT_V(8); PG8_WAIT_L(0); PG8_BAR; PG8_MMA(1, 0, At, B0); PG8_MMA(1, 1, At, B1); PG8_BAR; PG8_SCHED;
;             PG8_LDB(B0, 1, 0); PG8_LDB(B1, 1, 1); PG8_SCHED; PG8_LDA(At, 1, 0); PG8_STAGE(PG8_SA(0, 1), a2 + hstep, voffA);
;             PG8_WAIT_V(8); PG8_WAIT_L(0); PG8_BAR; PG8_MMA(0, 0, At, B0); PG8_MMA(0, 1, At, B1); PG8_BAR; PG8_SCHED;
	s_setprio 1
	s_waitcnt lgkmcnt(0)
	v_mfma_f32_16x16x32_bf16 v[62:65], v[148:151], v[180:183], v[62:65]
	v_mfma_f32_16x16x32_bf16 v[58:61], v[156:159], v[180:183], v[58:61]
	v_mfma_f32_16x16x32_bf16 v[42:45], v[156:159], v[194:197], v[42:45]
	v_mfma_f32_16x16x32_bf16 v[46:49], v[148:151], v[194:197], v[46:49]
	v_mfma_f32_16x16x32_bf16 v[30:33], v[148:151], v[216:219], v[30:33]
	v_mfma_f32_16x16x32_bf16 v[26:29], v[156:159], v[216:219], v[26:29]
	v_mfma_f32_16x16x32_bf16 v[10:13], v[156:159], v[224:227], v[10:13]
	v_mfma_f32_16x16x32_bf16 v[14:17], v[148:151], v[224:227], v[14:17]
	v_mfma_f32_16x16x32_bf16 v[62:65], v[152:155], v[190:193], v[62:65]
	v_mfma_f32_16x16x32_bf16 v[58:61], v[160:163], v[190:193], v[58:61]
	v_mfma_f32_16x16x32_bf16 v[42:45], v[160:163], v[198:201], v[42:45]
	v_mfma_f32_16x16x32_bf16 v[46:49], v[152:155], v[198:201], v[46:49]
	v_mfma_f32_16x16x32_bf16 v[30:33], v[152:155], v[220:223], v[30:33]
	v_mfma_f32_16x16x32_bf16 v[26:29], v[160:163], v[220:223], v[26:29]
	v_mfma_f32_16x16x32_bf16 v[10:13], v[160:163], v[228:231], v[10:13]
	v_mfma_f32_16x16x32_bf16 v[14:17], v[152:155], v[228:231], v[14:17]
	s_setprio 0
	s_setprio 1
	v_mfma_f32_16x16x32_bf16 v[54:57], v[164:167], v[180:183], v[54:57]
	v_mfma_f32_16x16x32_bf16 v[50:53], v[172:175], v[180:183], v[50:53]
	v_mfma_f32_16x16x32_bf16 v[34:37], v[172:175], v[194:197], v[34:37]
	v_mfma_f32_16x16x32_bf16 v[38:41], v[164:167], v[194:197], v[38:41]
	v_mfma_f32_16x16x32_bf16 v[22:25], v[164:167], v[216:219], v[22:25]
	v_mfma_f32_16x16x32_bf16 v[18:21], v[172:175], v[216:219], v[18:21]
	v_mfma_f32_16x16x32_bf16 v[2:5], v[172:175], v[224:227], v[2:5]
	v_mfma_f32_16x16x32_bf16 v[6:9], v[164:167], v[224:227], v[6:9]
	v_mfma_f32_16x16x32_bf16 v[54:57], v[168:171], v[190:193], v[54:57]
	v_mfma_f32_16x16x32_bf16 v[50:53], v[176:179], v[190:193], v[50:53]
	v_mfma_f32_16x16x32_bf16 v[34:37], v[176:179], v[198:201], v[34:37]
	v_mfma_f32_16x16x32_bf16 v[38:41], v[168:171], v[198:201], v[38:41]
	v_mfma_f32_16x16x32_bf16 v[22:25], v[168:171], v[220:223], v[22:25]
	v_mfma_f32_16x16x32_bf16 v[18:21], v[176:179], v[220:223], v[18:21]
	v_mfma_f32_16x16x32_bf16 v[2:5], v[176:179], v[228:231], v[2:5]
	v_mfma_f32_16x16x32_bf16 v[6:9], v[168:171], v[228:231], v[6:9]
	s_setprio 0
	s_barrier
	s_add_i32 s12, 0, 0x18000
	s_add_i32 s13, 0, 0x1c000
	v_add_u32_e32 v160, s12, v187
	v_add_u32_e32 v176, s13, v187
	ds_read_b128 v[148:151], v160
	ds_read_b128 v[152:155], v160 offset:1024
	ds_read_b128 v[156:159], v160 offset:2048
	ds_read_b128 v[160:163], v160 offset:3072
	ds_read_b128 v[164:167], v176
	ds_read_b128 v[168:171], v176 offset:1024
	ds_read_b128 v[172:175], v176 offset:2048
	ds_read_b128 v[176:179], v176 offset:3072
	s_add_u32 s10, s26, 0x80000
	s_addc_u32 s11, s27, 0
	s_mov_b32 m0, s63
	v_lshl_add_u64 v[238:239], s[10:11], 0, v[0:1]
	ds_read_b128 v[180:183], v189 offset:32768
	ds_read_b128 v[190:193], v189 offset:33792
	ds_read_b128 v[194:197], v189 offset:34816
	ds_read_b128 v[198:201], v189 offset:35840
	ds_read_b128 v[216:219], v189 offset:36864
	ds_read_b128 v[220:223], v189 offset:37888
	ds_read_b128 v[224:227], v189 offset:38912
	ds_read_b128 v[228:231], v189 offset:39936
	global_load_lds_dwordx4 v[238:239], off
	v_lshl_add_u64 v[238:239], s[10:11], 0, v[142:143]
	s_mov_b32 m0, s64
	s_nop 0
	global_load_lds_dwordx4 v[238:239], off
	s_waitcnt vmcnt(8)
	s_waitcnt lgkmcnt(0)
	s_barrier
	s_setprio 1
	s_waitcnt lgkmcnt(0)
	v_mfma_f32_16x16x32_bf16 v[126:129], v[148:151], v[180:183], v[126:129]
	v_mfma_f32_16x16x32_bf16 v[122:125], v[156:159], v[180:183], v[122:125]
	v_mfma_f32_16x16x32_bf16 v[106:109], v[156:159], v[194:197], v[106:109]
	v_mfma_f32_16x16x32_bf16 v[110:113], v[148:151], v[194:197], v[110:113]
	v_mfma_f32_16x16x32_bf16 v[94:97], v[148:151], v[216:219], v[94:97]
	v_mfma_f32_16x16x32_bf16 v[90:93], v[156:159], v[216:219], v[90:93]
	v_mfma_f32_16x16x32_bf16 v[74:77], v[156:159], v[224:227], v[74:77]
	v_mfma_f32_16x16x32_bf16 v[78:81], v[148:151], v[224:227], v[78:81]
	v_mfma_f32_16x16x32_bf16 v[126:129], v[152:155], v[190:193], v[126:129]
	v_mfma_f32_16x16x32_bf16 v[122:125], v[160:163], v[190:193], v[122:125]
	v_mfma_f32_16x16x32_bf16 v[106:109], v[160:163], v[198:201], v[106:109]
	v_mfma_f32_16x16x32_bf16 v[110:113], v[152:155], v[198:201], v[110:113]
	v_mfma_f32_16x16x32_bf16 v[94:97], v[152:155], v[220:223], v[94:97]
	v_mfma_f32_16x16x32_bf16 v[90:93], v[160:163], v[220:223], v[90:93]
	v_mfma_f32_16x16x32_bf16 v[74:77], v[160:163], v[228:231], v[74:77]
	v_mfma_f32_16x16x32_bf16 v[78:81], v[152:155], v[228:231], v[78:81]
	s_setprio 0
	s_setprio 1
	v_mfma_f32_16x16x32_bf16 v[118:121], v[164:167], v[180:183], v[118:121]
	v_mfma_f32_16x16x32_bf16 v[114:117], v[172:175], v[180:183], v[114:117]
	v_mfma_f32_16x16x32_bf16 v[98:101], v[172:175], v[194:197], v[98:101]
	v_mfma_f32_16x16x32_bf16 v[102:105], v[164:167], v[194:197], v[102:105]
	v_mfma_f32_16x16x32_bf16 v[86:89], v[164:167], v[216:219], v[86:89]
	v_mfma_f32_16x16x32_bf16 v[82:85], v[172:175], v[216:219], v[82:85]
	v_mfma_f32_16x16x32_bf16 v[66:69], v[172:175], v[224:227], v[66:69]
	v_mfma_f32_16x16x32_bf16 v[70:73], v[164:167], v[224:227], v[70:73]
	v_mfma_f32_16x16x32_bf16 v[118:121], v[168:171], v[190:193], v[118:121]
	v_mfma_f32_16x16x32_bf16 v[114:117], v[176:179], v[190:193], v[114:117]
	v_mfma_f32_16x16x32_bf16 v[98:101], v[176:179], v[198:201], v[98:101]
	v_mfma_f32_16x16x32_bf16 v[102:105], v[168:171], v[198:201], v[102:105]
	v_mfma_f32_16x16x32_bf16 v[86:89], v[168:171], v[220:223], v[86:89]
	v_mfma_f32_16x16x32_bf16 v[82:85], v[176:179], v[220:223], v[82:85]
	v_mfma_f32_16x16x32_bf16 v[66:69], v[176:179], v[228:231], v[66:69]
	v_mfma_f32_16x16x32_bf16 v[70:73], v[168:171], v[228:231], v[70:73]
	s_setprio 0
	s_barrier
; #define PG8_STAGE(bufoff, gbase, voff) do { _Pragma("unroll") for (int _i = 0; _i < 2; ++_i) \
;         __builtin_amdgcn_global_load_lds((const unsigned*)((const char*)(gbase) + (voff)[_i]), (PG8_LAS unsigned*)(lds + (bufoff) + ldsw + _i * 8192), 16, 0, 0); } while (0)
; #define PG8_LDA(dst, b, h) do { _Pragma("unroll") for (int m = 0; m < 4; ++m) _Pragma("unroll") for (int k = 0; k < 2; ++k) dst[m][k] = *(const PG8_LAS bf16x8*)(lds + PG8_SA(b, h) + aoff + m * 2048 + k * 1024); } while (0)
; #define PG8_MMA(ai, bj, At, Bt) do { __builtin_amdgcn_s_setprio(1); _Pragma("unroll") for (int m = 0; m < 4; ++m) _Pragma("unroll") for (int n = 0; n < 2; ++n) _Pragma("unroll") for (int k = 0; k < 2; ++k) \
;         acc[ai][bj][m][n] = __builtin_amdgcn_mfma_f32_16x16x32_bf16(Bt[n][k], At[m][k], acc[ai][bj][m][n], 0, 0, 0); __builtin_amdgcn_s_setprio(0); } while (0)
; #define PG8_WAIT_V(n) asm volatile("s_waitcnt vmcnt(" #n ")" ::: "memory")
; #define PG8_WAIT_L(n) asm volatile("s_waitcnt lgkmcnt(" #n ")" ::: "memory")
; #define PG8_BAR __builtin_amdgcn_s_barrier()
; #define PG8_SCHED __builtin_amdgcn_sched_barrier(0)
; template <class Epi, class Sched, bool ALIGN_EPI = false, bool SP2 = false>
; __device__ __forceinline__ void gemm_phase(PG8_LAS unsigned char* lds, const Gemm g, const Sched& S, const Epi& E) {
;     ...
;             PG8_LDA(At, 1, 1); PG8_STAGE(PG8_SB(1, 0), b3, voffB); PG8_STAGE(PG8_SB(1, 1), b3 + hstep, voffB); PG8_STAGE(PG8_SA(1, 0), a3, voffA);
;             PG8_WAIT_V(8); PG8_WAIT_L(0); PG8_BAR; PG8_MMA(1, 0, At, B0); PG8_MMA(1, 1, At, B1); PG8_BAR; PG8_SCHED;
	s_add_i32 s10, s12, s60
	v_lshl_add_u64 v[184:185], v[184:185], 0, s[30:31]
	s_mov_b32 m0, s10
	ds_read_b128 v[180:183], v189 offset:49152
	ds_read_b128 v[190:193], v189 offset:50176
	ds_read_b128 v[194:197], v189 offset:51200
	ds_read_b128 v[198:201], v189 offset:52224
	ds_read_b128 v[216:219], v189 offset:53248
	ds_read_b128 v[220:223], v189 offset:54272
	ds_read_b128 v[224:227], v189 offset:55296
	ds_read_b128 v[228:231], v189 offset:56320
	global_load_lds_dwordx4 v[184:185], off
	s_add_i32 m0, s10, 0x2000
	s_add_u32 s10, s24, 0x80080
	v_lshl_add_u64 v[184:185], v[232:233], 0, s[30:31]
	s_addc_u32 s11, s25, 0
	s_add_i32 s12, s13, s60
	global_load_lds_dwordx4 v[184:185], off
	v_lshl_add_u64 v[184:185], s[10:11], 0, v[0:1]
	s_mov_b32 m0, s12
	s_nop 0
	global_load_lds_dwordx4 v[184:185], off
	v_lshl_add_u64 v[184:185], s[10:11], 0, v[142:143]
	s_add_i32 m0, s12, 0x2000
	s_nop 0
	global_load_lds_dwordx4 v[184:185], off
	v_lshl_add_u64 v[184:185], v[234:235], 0, s[30:31]
	s_mov_b32 m0, s65
	s_nop 0
	global_load_lds_dwordx4 v[184:185], off
	v_lshl_add_u64 v[184:185], v[236:237], 0, s[30:31]
	s_mov_b32 m0, s66
	s_nop 0
	global_load_lds_dwordx4 v[184:185], off
	s_waitcnt vmcnt(8)
	s_waitcnt lgkmcnt(0)
	s_barrier
	s_setprio 1
	s_waitcnt lgkmcnt(0)
	v_mfma_f32_16x16x32_bf16 v[62:65], v[148:151], v[180:183], v[62:65]
	v_mfma_f32_16x16x32_bf16 v[58:61], v[156:159], v[180:183], v[58:61]
	v_mfma_f32_16x16x32_bf16 v[42:45], v[156:159], v[194:197], v[42:45]
	v_mfma_f32_16x16x32_bf16 v[46:49], v[148:151], v[194:197], v[46:49]
	v_mfma_f32_16x16x32_bf16 v[30:33], v[148:151], v[216:219], v[30:33]
	v_mfma_f32_16x16x32_bf16 v[26:29], v[156:159], v[216:219], v[26:29]
	v_mfma_f32_16x16x32_bf16 v[10:13], v[156:159], v[224:227], v[10:13]
	v_mfma_f32_16x16x32_bf16 v[14:17], v[148:151], v[224:227], v[14:17]
	v_mfma_f32_16x16x32_bf16 v[62:65], v[152:155], v[190:193], v[62:65]
	v_mfma_f32_16x16x32_bf16 v[58:61], v[160:163], v[190:193], v[58:61]
	v_mfma_f32_16x16x32_bf16 v[42:45], v[160:163], v[198:201], v[42:45]
	v_mfma_f32_16x16x32_bf16 v[46:49], v[152:155], v[198:201], v[46:49]
	v_mfma_f32_16x16x32_bf16 v[30:33], v[152:155], v[220:223], v[30:33]
	v_mfma_f32_16x16x32_bf16 v[26:29], v[160:163], v[220:223], v[26:29]
	v_mfma_f32_16x16x32_bf16 v[10:13], v[160:163], v[228:231], v[10:13]
	v_mfma_f32_16x16x32_bf16 v[14:17], v[152:155], v[228:231], v[14:17]
	s_setprio 0
	s_setprio 1
	v_mfma_f32_16x16x32_bf16 v[54:57], v[164:167], v[180:183], v[54:57]
	v_mfma_f32_16x16x32_bf16 v[50:53], v[172:175], v[180:183], v[50:53]
	v_mfma_f32_16x16x32_bf16 v[34:37], v[172:175], v[194:197], v[34:37]
	v_mfma_f32_16x16x32_bf16 v[38:41], v[164:167], v[194:197], v[38:41]
	v_mfma_f32_16x16x32_bf16 v[22:25], v[164:167], v[216:219], v[22:25]
	v_mfma_f32_16x16x32_bf16 v[18:21], v[172:175], v[216:219], v[18:21]
	v_mfma_f32_16x16x32_bf16 v[2:5], v[172:175], v[224:227], v[2:5]
	v_mfma_f32_16x16x32_bf16 v[6:9], v[164:167], v[224:227], v[6:9]
	v_mfma_f32_16x16x32_bf16 v[54:57], v[168:171], v[190:193], v[54:57]
	v_mfma_f32_16x16x32_bf16 v[50:53], v[176:179], v[190:193], v[50:53]
	v_mfma_f32_16x16x32_bf16 v[34:37], v[176:179], v[198:201], v[34:37]
	v_mfma_f32_16x16x32_bf16 v[38:41], v[168:171], v[198:201], v[38:41]
	v_mfma_f32_16x16x32_bf16 v[22:25], v[168:171], v[220:223], v[22:25]
	v_mfma_f32_16x16x32_bf16 v[18:21], v[176:179], v[220:223], v[18:21]
	v_mfma_f32_16x16x32_bf16 v[2:5], v[176:179], v[228:231], v[2:5]
	v_mfma_f32_16x16x32_bf16 v[6:9], v[168:171], v[228:231], v[6:9]
	s_setprio 0
	s_barrier
	s_add_i32 s22, s22, 2
	s_add_u32 s14, s14, 0x100
	s_addc_u32 s15, s15, 0
	s_cmp_gt_u32 s22, 29
	s_mov_b64 s[16:17], s[18:19]
	s_cbranch_scc0 .LBB0_601
; __device__ __forceinline__ unsigned cvt_pk_bf16(float lo, float hi) { unsigned r; asm volatile("v_cvt_pk_bf16_f32 %0, %1, %2" : "=v"(r) : "v"(lo), "v"(hi)); return r; }
;     __device__ __forceinline__ void operator()(const f32x4 (&acc)[2][2][4][2], const Unit& u, int wr, int wc, int fr, int fq) const {
;         const int row0 = u.pm * BM + wr * 64 + fr; const int col0 = u.pn * BM + wc * 32 + 4 * fq;
; #pragma unroll
;         for (int ai = 0; ai < 2; ++ai) {
;             u32x2 bv[4][2][2];
; #pragma unroll
;             for (int m = 0; m < 4; ++m) { const size_t off = (size_t)(row0 + ai * HALF + m * 16) * ldc + col0;
; #pragma unroll
;                 for (int bj = 0; bj < 2; ++bj)
; #pragma unroll
;                     for (int n = 0; n < 2; ++n) bv[m][bj][n] = *(const u32x2*)(xb + off + bj * HALF + n * 16); }
;             asm volatile("" ::: "memory");
; #pragma unroll
;             for (int m = 0; m < 4; ++m) {
;                 const int row = row0 + ai * HALF + m * 16;
;                 const size_t off = (size_t)row * ldc + col0;
;                 float s = 0.f;
; #pragma unroll
;                 for (int bj = 0; bj < 2; ++bj)
; #pragma unroll
;                     for (int n = 0; n < 2; ++n) {
;                         const size_t c = off + bj * HALF + n * 16;
;                         const u32x2 w0 = bv[m][bj][n];
;                         const f32x4 b = {__uint_as_float(w0.x << 16), __uint_as_float(w0.x & 0xffff0000u), __uint_as_float(w0.y << 16), __uint_as_float(w0.y & 0xffff0000u)};
;                         const f32x4 o = b + acc[ai][bj][m][n];
;                         if (fin) { *(f32x4*)(outf + c) = o; }
;                         else { u32x2 w; w.x = cvt_pk_bf16(o[0], o[1]); w.y = cvt_pk_bf16(o[2], o[3]); *(u32x2*)(xb + c) = w;
;                                s += (o[0] * o[0] + o[1] * o[1]) + (o[2] * o[2] + o[3] * o[3]); }
;                     }
;                 if (!fin) { s += __shfl_xor(s, 16); s += __shfl_xor(s, 32); if (fq == 0) unsafeAtomicAdd(ssq + row, s); }
	v_lshl_or_b32 v148, s2, 8, v188
	v_lshl_add_u32 v152, s4, 8, v186
	v_ashrrev_i32_e32 v149, 31, v148
	v_lshlrev_b64 v[190:191], 1, v[148:149]
	v_ashrrev_i32_e32 v153, 31, v152
	v_lshl_add_u64 v[150:151], s[48:49], 0, v[190:191]
	v_lshlrev_b64 v[154:155], 12, v[152:153]
	v_lshl_add_u64 v[156:157], v[150:151], 0, v[154:155]
	global_load_dwordx2 v[192:193], v[156:157], off
	global_load_dwordx2 v[194:195], v[156:157], off offset:32
	global_load_dwordx2 v[196:197], v[156:157], off offset:256
	global_load_dwordx2 v[198:199], v[156:157], off offset:288
	v_or_b32_e32 v184, 16, v152
	v_ashrrev_i32_e32 v185, 31, v184
	v_lshlrev_b64 v[156:157], 12, v[184:185]
	v_or_b32_e32 v174, 32, v152
	v_lshl_add_u64 v[156:157], v[150:151], 0, v[156:157]
	v_ashrrev_i32_e32 v175, 31, v174
	global_load_dwordx2 v[182:183], v[156:157], off
	global_load_dwordx2 v[180:181], v[156:157], off offset:32
	global_load_dwordx2 v[178:179], v[156:157], off offset:256
	global_load_dwordx2 v[176:177], v[156:157], off offset:288
	v_lshlrev_b64 v[156:157], 12, v[174:175]
	v_or_b32_e32 v158, 48, v152
	v_lshl_add_u64 v[156:157], v[150:151], 0, v[156:157]
	v_ashrrev_i32_e32 v159, 31, v158
	global_load_dwordx2 v[172:173], v[156:157], off
	global_load_dwordx2 v[170:171], v[156:157], off offset:32
	global_load_dwordx2 v[166:167], v[156:157], off offset:256
	global_load_dwordx2 v[162:163], v[156:157], off offset:288
	v_lshlrev_b64 v[156:157], 12, v[158:159]
	v_lshl_add_u64 v[156:157], v[150:151], 0, v[156:157]
	global_load_dwordx2 v[168:169], v[156:157], off
	global_load_dwordx2 v[164:165], v[156:157], off offset:32
	global_load_dwordx2 v[160:161], v[156:157], off offset:256
	s_nop 0
	global_load_dwordx2 v[156:157], v[156:157], off offset:288
	s_waitcnt vmcnt(0)
	v_lshlrev_b32_e32 v200, 16, v192
	v_and_b32_e32 v201, 0xffff0000, v192
	v_lshlrev_b32_e32 v192, 16, v193
	v_and_b32_e32 v193, 0xffff0000, v193
	v_pk_add_f32 v[126:127], v[126:127], v[200:201]
	v_pk_add_f32 v[128:129], v[128:129], v[192:193]
	v_cvt_pk_bf16_f32 v192, v126, v127
	v_mul_f32_e32 v127, v127, v127
	v_lshl_add_u64 v[200:201], s[48:49], 0, v[154:155]
	v_fmac_f32_e32 v127, v126, v126
	v_mul_f32_e32 v126, v129, v129
	v_lshl_add_u64 v[190:191], v[200:201], 0, v[190:191]
	v_fmac_f32_e32 v126, v128, v128
	v_cvt_pk_bf16_f32 v193, v128, v129
	global_store_dwordx2 v[190:191], v[192:193], off
	v_add_f32_e32 v192, v127, v126
	v_lshlrev_b32_e32 v126, 16, v194
	v_and_b32_e32 v127, 0xffff0000, v194
	v_lshlrev_b32_e32 v128, 16, v195
	v_and_b32_e32 v129, 0xffff0000, v195
	v_pk_add_f32 v[122:123], v[122:123], v[126:127]
	v_pk_add_f32 v[124:125], v[124:125], v[128:129]
	v_cvt_pk_bf16_f32 v126, v122, v123
	v_mul_f32_e32 v123, v123, v123
	v_fmac_f32_e32 v123, v122, v122
	v_mul_f32_e32 v122, v125, v125
	v_fmac_f32_e32 v122, v124, v124
	v_add_f32_e32 v122, v123, v122
	v_cvt_pk_bf16_f32 v127, v124, v125
	global_store_dwordx2 v[190:191], v[126:127], off offset:32
	v_add_f32_e32 v126, v192, v122
	v_lshlrev_b32_e32 v122, 16, v196
	v_and_b32_e32 v123, 0xffff0000, v196
	v_lshlrev_b32_e32 v124, 16, v197
	v_and_b32_e32 v125, 0xffff0000, v197
	v_pk_add_f32 v[118:119], v[118:119], v[122:123]
	v_pk_add_f32 v[120:121], v[120:121], v[124:125]
	v_cvt_pk_bf16_f32 v122, v118, v119
	v_mul_f32_e32 v119, v119, v119
	v_fmac_f32_e32 v119, v118, v118
	v_mul_f32_e32 v118, v121, v121
	v_fmac_f32_e32 v118, v120, v120
	v_add_f32_e32 v118, v119, v118
	v_cvt_pk_bf16_f32 v123, v120, v121
	global_store_dwordx2 v[190:191], v[122:123], off offset:256
	v_add_f32_e32 v122, v126, v118
	v_lshlrev_b32_e32 v118, 16, v198
	v_and_b32_e32 v119, 0xffff0000, v198
	v_lshlrev_b32_e32 v120, 16, v199
	v_and_b32_e32 v121, 0xffff0000, v199
	v_pk_add_f32 v[114:115], v[114:115], v[118:119]
	v_pk_add_f32 v[116:117], v[116:117], v[120:121]
	v_cvt_pk_bf16_f32 v118, v114, v115
	v_mul_f32_e32 v115, v115, v115
	v_fmac_f32_e32 v115, v114, v114
	v_mul_f32_e32 v114, v117, v117
	v_cvt_pk_bf16_f32 v119, v116, v117
	v_fmac_f32_e32 v114, v116, v116
	v_and_b32_e32 v116, 64, v208
	v_add_f32_e32 v114, v115, v114
	v_xor_b32_e32 v115, 16, v208
	v_add_u32_e32 v117, 64, v116
	v_cmp_lt_i32_e32 vcc, v115, v117
	v_add_f32_e32 v114, v122, v114
	global_store_dwordx2 v[190:191], v[118:119], off offset:288
	v_cndmask_b32_e32 v115, v208, v115, vcc
	v_lshlrev_b32_e32 v116, 2, v115
	ds_bpermute_b32 v115, v116, v114
	s_waitcnt lgkmcnt(0)
	v_add_f32_e32 v118, v114, v115
	v_xor_b32_e32 v114, 32, v208
	v_cmp_lt_i32_e32 vcc, v114, v117
	s_nop 1
	v_cndmask_b32_e32 v114, v208, v114, vcc
	v_lshlrev_b32_e32 v117, 2, v114
	ds_bpermute_b32 v119, v117, v118
	v_lshl_add_u64 v[114:115], v[152:153], 2, s[50:51]
	s_and_saveexec_b64 s[16:17], s[42:43]
	s_cbranch_execz .LBB0_604
	s_waitcnt lgkmcnt(0)
	v_add_f32_e32 v118, v118, v119
	global_atomic_add_f32 v[114:115], v118, off

; #define PG8_STAGE(bufoff, gbase, voff) do { _Pragma("unroll") for (int _i = 0; _i < 2; ++_i) \
;         __builtin_amdgcn_global_load_lds((const unsigned*)((const char*)(gbase) + (voff)[_i]), (PG8_LAS unsigned*)(lds + (bufoff) + ldsw + _i * 8192), 16, 0, 0); } while (0)
; #define PG8_LDA(dst, b, h) do { _Pragma("unroll") for (int m = 0; m < 4; ++m) _Pragma("unroll") for (int k = 0; k < 2; ++k) dst[m][k] = *(const PG8_LAS bf16x8*)(lds + PG8_SA(b, h) + aoff + m * 2048 + k * 1024); } while (0)
; #define PG8_LDB(dst, b, h) do { _Pragma("unroll") for (int n = 0; n < 2; ++n) _Pragma("unroll") for (int k = 0; k < 2; ++k) dst[n][k] = *(const PG8_LAS bf16x8*)(lds + PG8_SB(b, h) + boff + n * 2048 + k * 1024); } while (0)
; #define PG8_MMA(ai, bj, At, Bt) do { __builtin_amdgcn_s_setprio(1); _Pragma("unroll") for (int m = 0; m < 4; ++m) _Pragma("unroll") for (int n = 0; n < 2; ++n) _Pragma("unroll") for (int k = 0; k < 2; ++k) \
;         acc[ai][bj][m][n] = __builtin_amdgcn_mfma_f32_16x16x32_bf16(Bt[n][k], At[m][k], acc[ai][bj][m][n], 0, 0, 0); __builtin_amdgcn_s_setprio(0); } while (0)
; #define PG8_WAIT_V(n) asm volatile("s_waitcnt vmcnt(" #n ")" ::: "memory")
; #define PG8_WAIT_L(n) asm volatile("s_waitcnt lgkmcnt(" #n ")" ::: "memory")
; template <class Epi, class Sched, bool ALIGN_EPI = false, bool SP2 = false>
; __device__ __forceinline__ void gemm_phase(PG8_LAS unsigned char* lds, const Gemm g, const Sched& S, const Epi& E) {
;     ...
;             const bool last = (t == nt - 2);
;             const char* a1 = cA + (size_t)(t + 1) * kstep;
;             const char* a2 = last ? nA : cA + (size_t)(t + 2) * kstep; const char* b2 = last ? nB : cB + (size_t)(t + 2) * kstep;
;             const char* a3 = a2 + kstep; const char* b3 = b2 + kstep;
;             if (last && has_next) S.a_ready(nxt);
;             if constexpr (SP2) {
;             PG8_LDB(B0, 0, 0); PG8_LDB(B1, 0, 1); PG8_SCHED; PG8_LDA(At, 0, 0); PG8_STAGE(PG8_SA(1, 1), a1 + hstep, voffA);
;             PG8_WAIT_V(8); PG8_WAIT_L(0); PG8_BAR; PG8_MMA(0, 0, At, B0); PG8_MMA(0, 1, At, B1); PG8_BAR; PG8_SCHED;
;             PG8_LDA(At, 0, 1); PG8_STAGE(PG8_SB(0, 0), b2, voffB); PG8_STAGE(PG8_SB(0, 1), b2 + hstep, voffB); PG8_STAGE(PG8_SA(0, 0), a2, voffA);
;             PG8_WAIT_V(8); PG8_WAIT_L(0); PG8_BAR; PG8_MMA(1, 0, At, B0); PG8_MMA(1, 1, At, B1); PG8_BAR; PG8_SCHED;
.LBB0_686:
	s_add_u32 s10, s16, 0xfff80080
	s_addc_u32 s11, s17, -1
	s_add_i32 s12, 0, 0x10000
	s_cmp_eq_u32 s22, 28
	s_cselect_b32 s25, s5, s11
	s_cselect_b32 s24, s7, s10
	v_add_u32_e32 v160, s12, v163
	s_cselect_b32 s19, s8, s15
	s_cselect_b32 s18, s9, s14
	s_add_i32 s13, 0, 0x14000
	ds_read_b128 v[152:155], v160
	ds_read_b128 v[156:159], v160 offset:1024
	ds_read_b128 v[166:169], v160 offset:2048
	ds_read_b128 v[170:173], v160 offset:3072
	v_add_u32_e32 v160, s13, v163
	ds_read_b128 v[174:177], v160
	ds_read_b128 v[178:181], v160 offset:1024
	ds_read_b128 v[182:185], v160 offset:2048
	ds_read_b128 v[186:189], v160 offset:3072
	v_lshl_add_u64 v[160:161], s[16:17], 0, v[148:149]
	s_add_i32 m0, s59, 0xc000
	ds_read_b128 v[190:193], v165
	ds_read_b128 v[194:197], v165 offset:1024
	ds_read_b128 v[198:201], v165 offset:2048
	ds_read_b128 v[216:219], v165 offset:3072
	ds_read_b128 v[220:223], v165 offset:4096
	ds_read_b128 v[224:227], v165 offset:5120
	ds_read_b128 v[228:231], v165 offset:6144
	ds_read_b128 v[232:235], v165 offset:7168
	global_load_lds_dwordx4 v[160:161], off
	v_lshl_add_u64 v[160:161], s[16:17], 0, v[150:151]
	s_add_i32 m0, s59, 0xe000
	s_nop 0
	global_load_lds_dwordx4 v[160:161], off
	s_waitcnt vmcnt(8)
	s_waitcnt lgkmcnt(0)
	s_barrier
	s_setprio 1
	s_waitcnt lgkmcnt(0)
	v_mfma_f32_16x16x32_bf16 v[126:129], v[152:155], v[190:193], v[126:129]
	v_mfma_f32_16x16x32_bf16 v[122:125], v[166:169], v[190:193], v[122:125]
	v_mfma_f32_16x16x32_bf16 v[106:109], v[166:169], v[198:201], v[106:109]
	v_mfma_f32_16x16x32_bf16 v[110:113], v[152:155], v[198:201], v[110:113]
	v_mfma_f32_16x16x32_bf16 v[94:97], v[152:155], v[220:223], v[94:97]
	v_mfma_f32_16x16x32_bf16 v[90:93], v[166:169], v[220:223], v[90:93]
	v_mfma_f32_16x16x32_bf16 v[74:77], v[166:169], v[228:231], v[74:77]
	v_mfma_f32_16x16x32_bf16 v[78:81], v[152:155], v[228:231], v[78:81]
	v_mfma_f32_16x16x32_bf16 v[126:129], v[156:159], v[194:197], v[126:129]
	v_mfma_f32_16x16x32_bf16 v[122:125], v[170:173], v[194:197], v[122:125]
	v_mfma_f32_16x16x32_bf16 v[106:109], v[170:173], v[216:219], v[106:109]
	v_mfma_f32_16x16x32_bf16 v[110:113], v[156:159], v[216:219], v[110:113]
	v_mfma_f32_16x16x32_bf16 v[94:97], v[156:159], v[224:227], v[94:97]
	v_mfma_f32_16x16x32_bf16 v[90:93], v[170:173], v[224:227], v[90:93]
	v_mfma_f32_16x16x32_bf16 v[74:77], v[170:173], v[232:235], v[74:77]
	v_mfma_f32_16x16x32_bf16 v[78:81], v[156:159], v[232:235], v[78:81]
	s_setprio 0
	s_setprio 1
	v_mfma_f32_16x16x32_bf16 v[118:121], v[174:177], v[190:193], v[118:121]
	v_mfma_f32_16x16x32_bf16 v[114:117], v[182:185], v[190:193], v[114:117]
	v_mfma_f32_16x16x32_bf16 v[98:101], v[182:185], v[198:201], v[98:101]
	v_mfma_f32_16x16x32_bf16 v[102:105], v[174:177], v[198:201], v[102:105]
	v_mfma_f32_16x16x32_bf16 v[86:89], v[174:177], v[220:223], v[86:89]
	v_mfma_f32_16x16x32_bf16 v[82:85], v[182:185], v[220:223], v[82:85]
	v_mfma_f32_16x16x32_bf16 v[66:69], v[182:185], v[228:231], v[66:69]
	v_mfma_f32_16x16x32_bf16 v[70:73], v[174:177], v[228:231], v[70:73]
	v_mfma_f32_16x16x32_bf16 v[118:121], v[178:181], v[194:197], v[118:121]
	v_mfma_f32_16x16x32_bf16 v[114:117], v[186:189], v[194:197], v[114:117]
	v_mfma_f32_16x16x32_bf16 v[98:101], v[186:189], v[216:219], v[98:101]
	v_mfma_f32_16x16x32_bf16 v[102:105], v[178:181], v[216:219], v[102:105]
	v_mfma_f32_16x16x32_bf16 v[86:89], v[178:181], v[224:227], v[86:89]
	v_mfma_f32_16x16x32_bf16 v[82:85], v[186:189], v[224:227], v[82:85]
	v_mfma_f32_16x16x32_bf16 v[66:69], v[186:189], v[232:235], v[66:69]
	v_mfma_f32_16x16x32_bf16 v[70:73], v[178:181], v[232:235], v[70:73]
	s_setprio 0
	s_barrier
	s_add_i32 s10, s12, s58
	v_lshl_add_u64 v[160:161], s[18:19], 0, v[0:1]
	s_mov_b32 m0, s10
	ds_read_b128 v[190:193], v165 offset:16384
	ds_read_b128 v[194:197], v165 offset:17408
	ds_read_b128 v[198:201], v165 offset:18432
	ds_read_b128 v[216:219], v165 offset:19456
	ds_read_b128 v[220:223], v165 offset:20480
	ds_read_b128 v[224:227], v165 offset:21504
	ds_read_b128 v[228:231], v165 offset:22528
	ds_read_b128 v[232:235], v165 offset:23552
	global_load_lds_dwordx4 v[160:161], off
	s_add_i32 m0, s10, 0x2000
	s_add_u32 s10, s18, 0x80000
	v_lshl_add_u64 v[236:237], s[18:19], 0, v[142:143]
	s_addc_u32 s11, s19, 0
	s_add_i32 s12, s13, s58
	global_load_lds_dwordx4 v[236:237], off
	v_lshl_add_u64 v[238:239], s[10:11], 0, v[0:1]
	s_mov_b32 m0, s12
	v_lshl_add_u64 v[240:241], s[24:25], 0, v[144:145]
	global_load_lds_dwordx4 v[238:239], off
	v_lshl_add_u64 v[238:239], s[10:11], 0, v[142:143]
	s_add_i32 m0, s12, 0x2000
	s_nop 0
	global_load_lds_dwordx4 v[238:239], off
	v_lshl_add_u64 v[238:239], s[24:25], 0, v[146:147]
	s_mov_b32 m0, s59
	s_nop 0
	global_load_lds_dwordx4 v[238:239], off
	s_mov_b32 m0, s60
	s_nop 0
	global_load_lds_dwordx4 v[240:241], off
	s_waitcnt vmcnt(8)
	s_waitcnt lgkmcnt(0)
	s_barrier
; #define PG8_STAGE(bufoff, gbase, voff) do { _Pragma("unroll") for (int _i = 0; _i < 2; ++_i) \
;         __builtin_amdgcn_global_load_lds((const unsigned*)((const char*)(gbase) + (voff)[_i]), (PG8_LAS unsigned*)(lds + (bufoff) + ldsw + _i * 8192), 16, 0, 0); } while (0)
; #define PG8_LDA(dst, b, h) do { _Pragma("unroll") for (int m = 0; m < 4; ++m) _Pragma("unroll") for (int k = 0; k < 2; ++k) dst[m][k] = *(const PG8_LAS bf16x8*)(lds + PG8_SA(b, h) + aoff + m * 2048 + k * 1024); } while (0)
; #define PG8_LDB(dst, b, h) do { _Pragma("unroll") for (int n = 0; n < 2; ++n) _Pragma("unroll") for (int k = 0; k < 2; ++k) dst[n][k] = *(const PG8_LAS bf16x8*)(lds + PG8_SB(b, h) + boff + n * 2048 + k * 1024); } while (0)
; #define PG8_MMA(ai, bj, At, Bt) do { __builtin_amdgcn_s_setprio(1); _Pragma("unroll") for (int m = 0; m < 4; ++m) _Pragma("unroll") for (int n = 0; n < 2; ++n) _Pragma("unroll") for (int k = 0; k < 2; ++k) \
;         acc[ai][bj][m][n] = __builtin_amdgcn_mfma_f32_16x16x32_bf16(Bt[n][k], At[m][k], acc[ai][bj][m][n], 0, 0, 0); __builtin_amdgcn_s_setprio(0); } while (0)
; #define PG8_WAIT_V(n) asm volatile("s_waitcnt vmcnt(" #n ")" ::: "memory")
; #define PG8_WAIT_L(n) asm volatile("s_waitcnt lgkmcnt(" #n ")" ::: "memory")
; #define PG8_BAR __builtin_amdgcn_s_barrier()
; #define PG8_SCHED __builtin_amdgcn_sched_barrier(0)
; template <class Epi, class Sched, bool ALIGN_EPI = false, bool SP2 = false>
; __device__ __forceinline__ void gemm_phase(PG8_LAS unsigned char* lds, const Gemm g, const Sched& S, const Epi& E) {
;     ...
;             PG8_WAIT_V(8); PG8_WAIT_L(0); PG8_BAR; PG8_MMA(1, 0, At, B0); PG8_MMA(1, 1, At, B1); PG8_BAR; PG8_SCHED;
;             PG8_LDB(B0, 1, 0); PG8_LDB(B1, 1, 1); PG8_SCHED; PG8_LDA(At, 1, 0); PG8_STAGE(PG8_SA(0, 1), a2 + hstep, voffA);
;             PG8_WAIT_V(8); PG8_WAIT_L(0); PG8_BAR; PG8_MMA(0, 0, At, B0); PG8_MMA(0, 1, At, B1); PG8_BAR; PG8_SCHED;
	s_setprio 1
	s_waitcnt lgkmcnt(0)
	v_mfma_f32_16x16x32_bf16 v[62:65], v[152:155], v[190:193], v[62:65]
	v_mfma_f32_16x16x32_bf16 v[58:61], v[166:169], v[190:193], v[58:61]
	v_mfma_f32_16x16x32_bf16 v[42:45], v[166:169], v[198:201], v[42:45]
	v_mfma_f32_16x16x32_bf16 v[46:49], v[152:155], v[198:201], v[46:49]
	v_mfma_f32_16x16x32_bf16 v[30:33], v[152:155], v[220:223], v[30:33]
	v_mfma_f32_16x16x32_bf16 v[26:29], v[166:169], v[220:223], v[26:29]
	v_mfma_f32_16x16x32_bf16 v[10:13], v[166:169], v[228:231], v[10:13]
	v_mfma_f32_16x16x32_bf16 v[14:17], v[152:155], v[228:231], v[14:17]
	v_mfma_f32_16x16x32_bf16 v[62:65], v[156:159], v[194:197], v[62:65]
	v_mfma_f32_16x16x32_bf16 v[58:61], v[170:173], v[194:197], v[58:61]
	v_mfma_f32_16x16x32_bf16 v[42:45], v[170:173], v[216:219], v[42:45]
	v_mfma_f32_16x16x32_bf16 v[46:49], v[156:159], v[216:219], v[46:49]
	v_mfma_f32_16x16x32_bf16 v[30:33], v[156:159], v[224:227], v[30:33]
	v_mfma_f32_16x16x32_bf16 v[26:29], v[170:173], v[224:227], v[26:29]
	v_mfma_f32_16x16x32_bf16 v[10:13], v[170:173], v[232:235], v[10:13]
	v_mfma_f32_16x16x32_bf16 v[14:17], v[156:159], v[232:235], v[14:17]
	s_setprio 0
	s_setprio 1
	v_mfma_f32_16x16x32_bf16 v[54:57], v[174:177], v[190:193], v[54:57]
	v_mfma_f32_16x16x32_bf16 v[50:53], v[182:185], v[190:193], v[50:53]
	v_mfma_f32_16x16x32_bf16 v[34:37], v[182:185], v[198:201], v[34:37]
	v_mfma_f32_16x16x32_bf16 v[38:41], v[174:177], v[198:201], v[38:41]
	v_mfma_f32_16x16x32_bf16 v[22:25], v[174:177], v[220:223], v[22:25]
	v_mfma_f32_16x16x32_bf16 v[18:21], v[182:185], v[220:223], v[18:21]
	v_mfma_f32_16x16x32_bf16 v[2:5], v[182:185], v[228:231], v[2:5]
	v_mfma_f32_16x16x32_bf16 v[6:9], v[174:177], v[228:231], v[6:9]
	v_mfma_f32_16x16x32_bf16 v[54:57], v[178:181], v[194:197], v[54:57]
	v_mfma_f32_16x16x32_bf16 v[50:53], v[186:189], v[194:197], v[50:53]
	v_mfma_f32_16x16x32_bf16 v[34:37], v[186:189], v[216:219], v[34:37]
	v_mfma_f32_16x16x32_bf16 v[38:41], v[178:181], v[216:219], v[38:41]
	v_mfma_f32_16x16x32_bf16 v[22:25], v[178:181], v[224:227], v[22:25]
	v_mfma_f32_16x16x32_bf16 v[18:21], v[186:189], v[224:227], v[18:21]
	v_mfma_f32_16x16x32_bf16 v[2:5], v[186:189], v[232:235], v[2:5]
	v_mfma_f32_16x16x32_bf16 v[6:9], v[178:181], v[232:235], v[6:9]
	s_setprio 0
	s_barrier
	s_add_i32 s12, 0, 0x18000
	s_add_i32 s13, 0, 0x1c000
	v_add_u32_e32 v170, s12, v163
	v_add_u32_e32 v186, s13, v163
	ds_read_b128 v[152:155], v170
	ds_read_b128 v[156:159], v170 offset:1024
	ds_read_b128 v[166:169], v170 offset:2048
	ds_read_b128 v[170:173], v170 offset:3072
	ds_read_b128 v[174:177], v186
	ds_read_b128 v[178:181], v186 offset:1024
	ds_read_b128 v[182:185], v186 offset:2048
	ds_read_b128 v[186:189], v186 offset:3072
	s_add_u32 s10, s24, 0x80000
	s_addc_u32 s11, s25, 0
	s_mov_b32 m0, s61
	v_lshl_add_u64 v[242:243], s[10:11], 0, v[146:147]
	ds_read_b128 v[190:193], v165 offset:32768
	ds_read_b128 v[194:197], v165 offset:33792
	ds_read_b128 v[198:201], v165 offset:34816
	ds_read_b128 v[216:219], v165 offset:35840
	ds_read_b128 v[220:223], v165 offset:36864
	ds_read_b128 v[224:227], v165 offset:37888
	ds_read_b128 v[228:231], v165 offset:38912
	ds_read_b128 v[232:235], v165 offset:39936
	global_load_lds_dwordx4 v[242:243], off
	v_lshl_add_u64 v[242:243], s[10:11], 0, v[144:145]
	s_mov_b32 m0, s62
	s_nop 0
	global_load_lds_dwordx4 v[242:243], off
	s_waitcnt vmcnt(8)
	s_waitcnt lgkmcnt(0)
	s_barrier
	s_setprio 1
	s_waitcnt lgkmcnt(0)
	v_mfma_f32_16x16x32_bf16 v[126:129], v[152:155], v[190:193], v[126:129]
	v_mfma_f32_16x16x32_bf16 v[122:125], v[166:169], v[190:193], v[122:125]
	v_mfma_f32_16x16x32_bf16 v[106:109], v[166:169], v[198:201], v[106:109]
	v_mfma_f32_16x16x32_bf16 v[110:113], v[152:155], v[198:201], v[110:113]
	v_mfma_f32_16x16x32_bf16 v[94:97], v[152:155], v[220:223], v[94:97]
	v_mfma_f32_16x16x32_bf16 v[90:93], v[166:169], v[220:223], v[90:93]
	v_mfma_f32_16x16x32_bf16 v[74:77], v[166:169], v[228:231], v[74:77]
	v_mfma_f32_16x16x32_bf16 v[78:81], v[152:155], v[228:231], v[78:81]
	v_mfma_f32_16x16x32_bf16 v[126:129], v[156:159], v[194:197], v[126:129]
	v_mfma_f32_16x16x32_bf16 v[122:125], v[170:173], v[194:197], v[122:125]
	v_mfma_f32_16x16x32_bf16 v[106:109], v[170:173], v[216:219], v[106:109]
	v_mfma_f32_16x16x32_bf16 v[110:113], v[156:159], v[216:219], v[110:113]
	v_mfma_f32_16x16x32_bf16 v[94:97], v[156:159], v[224:227], v[94:97]
	v_mfma_f32_16x16x32_bf16 v[90:93], v[170:173], v[224:227], v[90:93]
	v_mfma_f32_16x16x32_bf16 v[74:77], v[170:173], v[232:235], v[74:77]
	v_mfma_f32_16x16x32_bf16 v[78:81], v[156:159], v[232:235], v[78:81]
	s_setprio 0
	s_setprio 1
	v_mfma_f32_16x16x32_bf16 v[118:121], v[174:177], v[190:193], v[118:121]
	v_mfma_f32_16x16x32_bf16 v[114:117], v[182:185], v[190:193], v[114:117]
	v_mfma_f32_16x16x32_bf16 v[98:101], v[182:185], v[198:201], v[98:101]
	v_mfma_f32_16x16x32_bf16 v[102:105], v[174:177], v[198:201], v[102:105]
	v_mfma_f32_16x16x32_bf16 v[86:89], v[174:177], v[220:223], v[86:89]
	v_mfma_f32_16x16x32_bf16 v[82:85], v[182:185], v[220:223], v[82:85]
	v_mfma_f32_16x16x32_bf16 v[66:69], v[182:185], v[228:231], v[66:69]
	v_mfma_f32_16x16x32_bf16 v[70:73], v[174:177], v[228:231], v[70:73]
	v_mfma_f32_16x16x32_bf16 v[118:121], v[178:181], v[194:197], v[118:121]
	v_mfma_f32_16x16x32_bf16 v[114:117], v[186:189], v[194:197], v[114:117]
	v_mfma_f32_16x16x32_bf16 v[98:101], v[186:189], v[216:219], v[98:101]
	v_mfma_f32_16x16x32_bf16 v[102:105], v[178:181], v[216:219], v[102:105]
	v_mfma_f32_16x16x32_bf16 v[86:89], v[178:181], v[224:227], v[86:89]
	v_mfma_f32_16x16x32_bf16 v[82:85], v[186:189], v[224:227], v[82:85]
	v_mfma_f32_16x16x32_bf16 v[66:69], v[186:189], v[232:235], v[66:69]
	v_mfma_f32_16x16x32_bf16 v[70:73], v[178:181], v[232:235], v[70:73]
	s_setprio 0
	s_barrier
; #define PG8_STAGE(bufoff, gbase, voff) do { _Pragma("unroll") for (int _i = 0; _i < 2; ++_i) \
;         __builtin_amdgcn_global_load_lds((const unsigned*)((const char*)(gbase) + (voff)[_i]), (PG8_LAS unsigned*)(lds + (bufoff) + ldsw + _i * 8192), 16, 0, 0); } while (0)
; #define PG8_LDA(dst, b, h) do { _Pragma("unroll") for (int m = 0; m < 4; ++m) _Pragma("unroll") for (int k = 0; k < 2; ++k) dst[m][k] = *(const PG8_LAS bf16x8*)(lds + PG8_SA(b, h) + aoff + m * 2048 + k * 1024); } while (0)
; #define PG8_MMA(ai, bj, At, Bt) do { __builtin_amdgcn_s_setprio(1); _Pragma("unroll") for (int m = 0; m < 4; ++m) _Pragma("unroll") for (int n = 0; n < 2; ++n) _Pragma("unroll") for (int k = 0; k < 2; ++k) \
;         acc[ai][bj][m][n] = __builtin_amdgcn_mfma_f32_16x16x32_bf16(Bt[n][k], At[m][k], acc[ai][bj][m][n], 0, 0, 0); __builtin_amdgcn_s_setprio(0); } while (0)
; #define PG8_WAIT_V(n) asm volatile("s_waitcnt vmcnt(" #n ")" ::: "memory")
; #define PG8_WAIT_L(n) asm volatile("s_waitcnt lgkmcnt(" #n ")" ::: "memory")
; #define PG8_BAR __builtin_amdgcn_s_barrier()
; #define PG8_SCHED __builtin_amdgcn_sched_barrier(0)
; template <class Epi, class Sched, bool ALIGN_EPI = false, bool SP2 = false>
; __device__ __forceinline__ void gemm_phase(PG8_LAS unsigned char* lds, const Gemm g, const Sched& S, const Epi& E) {
;     ...
;             PG8_LDA(At, 1, 1); PG8_STAGE(PG8_SB(1, 0), b3, voffB); PG8_STAGE(PG8_SB(1, 1), b3 + hstep, voffB); PG8_STAGE(PG8_SA(1, 0), a3, voffA);
;             PG8_WAIT_V(8); PG8_WAIT_L(0); PG8_BAR; PG8_MMA(1, 0, At, B0); PG8_MMA(1, 1, At, B1); PG8_BAR; PG8_SCHED;
;     ...
;         if constexpr (ALIGN_EPI) { if (wr == 0) PG8_BAR; }
	s_add_i32 s10, s12, s58
	v_lshl_add_u64 v[160:161], v[160:161], 0, s[30:31]
	s_mov_b32 m0, s10
	ds_read_b128 v[190:193], v165 offset:49152
	ds_read_b128 v[194:197], v165 offset:50176
	ds_read_b128 v[198:201], v165 offset:51200
	ds_read_b128 v[216:219], v165 offset:52224
	ds_read_b128 v[220:223], v165 offset:53248
	ds_read_b128 v[224:227], v165 offset:54272
	ds_read_b128 v[228:231], v165 offset:55296
	ds_read_b128 v[232:235], v165 offset:56320
	global_load_lds_dwordx4 v[160:161], off
	s_add_i32 m0, s10, 0x2000
	s_add_u32 s10, s18, 0x80080
	v_lshl_add_u64 v[160:161], v[236:237], 0, s[30:31]
	s_addc_u32 s11, s19, 0
	s_add_i32 s12, s13, s58
	global_load_lds_dwordx4 v[160:161], off
	v_lshl_add_u64 v[160:161], s[10:11], 0, v[0:1]
	s_mov_b32 m0, s12
	s_nop 0
	global_load_lds_dwordx4 v[160:161], off
	v_lshl_add_u64 v[160:161], s[10:11], 0, v[142:143]
	s_add_i32 m0, s12, 0x2000
	s_nop 0
	global_load_lds_dwordx4 v[160:161], off
	v_lshl_add_u64 v[160:161], v[238:239], 0, s[30:31]
	s_mov_b32 m0, s63
	s_nop 0
	global_load_lds_dwordx4 v[160:161], off
	v_lshl_add_u64 v[160:161], v[240:241], 0, s[30:31]
	s_mov_b32 m0, s64
	s_nop 0
	global_load_lds_dwordx4 v[160:161], off
	s_waitcnt vmcnt(8)
	s_waitcnt lgkmcnt(0)
	s_barrier
	s_setprio 1
	s_waitcnt lgkmcnt(0)
	v_mfma_f32_16x16x32_bf16 v[62:65], v[152:155], v[190:193], v[62:65]
	v_mfma_f32_16x16x32_bf16 v[58:61], v[166:169], v[190:193], v[58:61]
	v_mfma_f32_16x16x32_bf16 v[42:45], v[166:169], v[198:201], v[42:45]
	v_mfma_f32_16x16x32_bf16 v[46:49], v[152:155], v[198:201], v[46:49]
	v_mfma_f32_16x16x32_bf16 v[30:33], v[152:155], v[220:223], v[30:33]
	v_mfma_f32_16x16x32_bf16 v[26:29], v[166:169], v[220:223], v[26:29]
	v_mfma_f32_16x16x32_bf16 v[10:13], v[166:169], v[228:231], v[10:13]
	v_mfma_f32_16x16x32_bf16 v[14:17], v[152:155], v[228:231], v[14:17]
	v_mfma_f32_16x16x32_bf16 v[62:65], v[156:159], v[194:197], v[62:65]
	v_mfma_f32_16x16x32_bf16 v[58:61], v[170:173], v[194:197], v[58:61]
	v_mfma_f32_16x16x32_bf16 v[42:45], v[170:173], v[216:219], v[42:45]
	v_mfma_f32_16x16x32_bf16 v[46:49], v[156:159], v[216:219], v[46:49]
	v_mfma_f32_16x16x32_bf16 v[30:33], v[156:159], v[224:227], v[30:33]
	v_mfma_f32_16x16x32_bf16 v[26:29], v[170:173], v[224:227], v[26:29]
	v_mfma_f32_16x16x32_bf16 v[10:13], v[170:173], v[232:235], v[10:13]
	v_mfma_f32_16x16x32_bf16 v[14:17], v[156:159], v[232:235], v[14:17]
	s_setprio 0
	s_setprio 1
	v_mfma_f32_16x16x32_bf16 v[54:57], v[174:177], v[190:193], v[54:57]
	v_mfma_f32_16x16x32_bf16 v[50:53], v[182:185], v[190:193], v[50:53]
	v_mfma_f32_16x16x32_bf16 v[34:37], v[182:185], v[198:201], v[34:37]
	v_mfma_f32_16x16x32_bf16 v[38:41], v[174:177], v[198:201], v[38:41]
	v_mfma_f32_16x16x32_bf16 v[22:25], v[174:177], v[220:223], v[22:25]
	v_mfma_f32_16x16x32_bf16 v[18:21], v[182:185], v[220:223], v[18:21]
	v_mfma_f32_16x16x32_bf16 v[2:5], v[182:185], v[228:231], v[2:5]
	v_mfma_f32_16x16x32_bf16 v[6:9], v[174:177], v[228:231], v[6:9]
	v_mfma_f32_16x16x32_bf16 v[54:57], v[178:181], v[194:197], v[54:57]
	v_mfma_f32_16x16x32_bf16 v[50:53], v[186:189], v[194:197], v[50:53]
	v_mfma_f32_16x16x32_bf16 v[34:37], v[186:189], v[216:219], v[34:37]
	v_mfma_f32_16x16x32_bf16 v[38:41], v[178:181], v[216:219], v[38:41]
	v_mfma_f32_16x16x32_bf16 v[22:25], v[178:181], v[224:227], v[22:25]
	v_mfma_f32_16x16x32_bf16 v[18:21], v[186:189], v[224:227], v[18:21]
	v_mfma_f32_16x16x32_bf16 v[2:5], v[186:189], v[232:235], v[2:5]
	v_mfma_f32_16x16x32_bf16 v[6:9], v[178:181], v[232:235], v[6:9]
	s_setprio 0
	s_barrier
	s_add_i32 s22, s22, 2
	s_add_u32 s16, s16, 0x100
	s_addc_u32 s17, s17, 0
	s_add_u32 s14, s14, 0x100
	s_addc_u32 s15, s15, 0
	s_cmp_gt_u32 s22, 29
	s_cbranch_scc0 .LBB0_686
	s_and_b64 vcc, exec, s[50:51]
	s_cbranch_vccz .LBB0_689
	s_barrier

; #define PG8_STAGE(bufoff, gbase, voff) do { _Pragma("unroll") for (int _i = 0; _i < 2; ++_i) \
;         __builtin_amdgcn_global_load_lds((const unsigned*)((const char*)(gbase) + (voff)[_i]), (PG8_LAS unsigned*)(lds + (bufoff) + ldsw + _i * 8192), 16, 0, 0); } while (0)
; #define PG8_LDA(dst, b, h) do { _Pragma("unroll") for (int m = 0; m < 4; ++m) _Pragma("unroll") for (int k = 0; k < 2; ++k) dst[m][k] = *(const PG8_LAS bf16x8*)(lds + PG8_SA(b, h) + aoff + m * 2048 + k * 1024); } while (0)
; #define PG8_LDB(dst, b, h) do { _Pragma("unroll") for (int n = 0; n < 2; ++n) _Pragma("unroll") for (int k = 0; k < 2; ++k) dst[n][k] = *(const PG8_LAS bf16x8*)(lds + PG8_SB(b, h) + boff + n * 2048 + k * 1024); } while (0)
; #define PG8_MMA(ai, bj, At, Bt) do { __builtin_amdgcn_s_setprio(1); _Pragma("unroll") for (int m = 0; m < 4; ++m) _Pragma("unroll") for (int n = 0; n < 2; ++n) _Pragma("unroll") for (int k = 0; k < 2; ++k) \
;         acc[ai][bj][m][n] = __builtin_amdgcn_mfma_f32_16x16x32_bf16(Bt[n][k], At[m][k], acc[ai][bj][m][n], 0, 0, 0); __builtin_amdgcn_s_setprio(0); } while (0)
; #define PG8_WAIT_V(n) asm volatile("s_waitcnt vmcnt(" #n ")" ::: "memory")
; #define PG8_WAIT_L(n) asm volatile("s_waitcnt lgkmcnt(" #n ")" ::: "memory")
; template <class Epi, class Sched, bool ALIGN_EPI = false, bool SP2 = false>
; __device__ __forceinline__ void gemm_phase(PG8_LAS unsigned char* lds, const Gemm g, const Sched& S, const Epi& E) {
;     ...
;             const bool last = (t == nt - 2);
;             const char* a1 = cA + (size_t)(t + 1) * kstep;
;             const char* a2 = last ? nA : cA + (size_t)(t + 2) * kstep; const char* b2 = last ? nB : cB + (size_t)(t + 2) * kstep;
;             const char* a3 = a2 + kstep; const char* b3 = b2 + kstep;
;             if (last && has_next) S.a_ready(nxt);
;             if constexpr (SP2) {
;             PG8_LDB(B0, 0, 0); PG8_LDB(B1, 0, 1); PG8_SCHED; PG8_LDA(At, 0, 0); PG8_STAGE(PG8_SA(1, 1), a1 + hstep, voffA);
;             PG8_WAIT_V(8); PG8_WAIT_L(0); PG8_BAR; PG8_MMA(0, 0, At, B0); PG8_MMA(0, 1, At, B1); PG8_BAR; PG8_SCHED;
;             PG8_LDA(At, 0, 1); PG8_STAGE(PG8_SB(0, 0), b2, voffB); PG8_STAGE(PG8_SB(0, 1), b2 + hstep, voffB); PG8_STAGE(PG8_SA(0, 0), a2, voffA);
;             PG8_WAIT_V(8); PG8_WAIT_L(0); PG8_BAR; PG8_MMA(1, 0, At, B0); PG8_MMA(1, 1, At, B1); PG8_BAR; PG8_SCHED;
.LBB0_758:
	s_add_u32 s18, s16, 0x100
	s_addc_u32 s19, s17, 0
	s_add_i32 s10, 0, 0x10000
	s_cmpk_eq_i32 s22, 0x7c
	s_cselect_b32 s27, s5, s19
	s_cselect_b32 s26, s7, s18
	s_cselect_b32 s25, s8, s15
	s_cselect_b32 s24, s9, s14
	s_add_i32 s12, 0, 0x14000
	v_add_u32_e32 v160, s10, v216
	v_add_u32_e32 v176, s12, v216
	ds_read_b128 v[148:151], v160
	ds_read_b128 v[152:155], v160 offset:1024
	ds_read_b128 v[156:159], v160 offset:2048
	ds_read_b128 v[160:163], v160 offset:3072
	ds_read_b128 v[164:167], v176
	ds_read_b128 v[168:171], v176 offset:1024
	ds_read_b128 v[172:175], v176 offset:2048
	ds_read_b128 v[176:179], v176 offset:3072
	v_lshl_add_u64 v[200:201], s[16:17], 0, v[144:145]
	s_add_i32 m0, s64, 0xc000
	ds_read_b128 v[180:183], v218
	ds_read_b128 v[184:187], v218 offset:1024
	ds_read_b128 v[188:191], v218 offset:2048
	ds_read_b128 v[192:195], v218 offset:3072
	ds_read_b128 v[196:199], v218 offset:4096
	ds_read_b128 v[220:223], v218 offset:5120
	ds_read_b128 v[224:227], v218 offset:6144
	ds_read_b128 v[228:231], v218 offset:7168
	global_load_lds_dwordx4 v[200:201], off
	v_lshl_add_u64 v[200:201], s[16:17], 0, v[146:147]
	s_add_i32 m0, s64, 0xe000
	s_nop 0
	global_load_lds_dwordx4 v[200:201], off
	s_waitcnt vmcnt(8)
	s_waitcnt lgkmcnt(0)
	s_barrier
	s_setprio 1
	s_waitcnt lgkmcnt(0)
	v_mfma_f32_16x16x32_bf16 v[126:129], v[148:151], v[180:183], v[126:129]
	v_mfma_f32_16x16x32_bf16 v[122:125], v[156:159], v[180:183], v[122:125]
	v_mfma_f32_16x16x32_bf16 v[106:109], v[156:159], v[188:191], v[106:109]
	v_mfma_f32_16x16x32_bf16 v[110:113], v[148:151], v[188:191], v[110:113]
	v_mfma_f32_16x16x32_bf16 v[94:97], v[148:151], v[196:199], v[94:97]
	v_mfma_f32_16x16x32_bf16 v[90:93], v[156:159], v[196:199], v[90:93]
	v_mfma_f32_16x16x32_bf16 v[74:77], v[156:159], v[224:227], v[74:77]
	v_mfma_f32_16x16x32_bf16 v[78:81], v[148:151], v[224:227], v[78:81]
	v_mfma_f32_16x16x32_bf16 v[126:129], v[152:155], v[184:187], v[126:129]
	v_mfma_f32_16x16x32_bf16 v[122:125], v[160:163], v[184:187], v[122:125]
	v_mfma_f32_16x16x32_bf16 v[106:109], v[160:163], v[192:195], v[106:109]
	v_mfma_f32_16x16x32_bf16 v[110:113], v[152:155], v[192:195], v[110:113]
	v_mfma_f32_16x16x32_bf16 v[94:97], v[152:155], v[220:223], v[94:97]
	v_mfma_f32_16x16x32_bf16 v[90:93], v[160:163], v[220:223], v[90:93]
	v_mfma_f32_16x16x32_bf16 v[74:77], v[160:163], v[228:231], v[74:77]
	v_mfma_f32_16x16x32_bf16 v[78:81], v[152:155], v[228:231], v[78:81]
	s_setprio 0
	s_setprio 1
	v_mfma_f32_16x16x32_bf16 v[118:121], v[164:167], v[180:183], v[118:121]
	v_mfma_f32_16x16x32_bf16 v[114:117], v[172:175], v[180:183], v[114:117]
	v_mfma_f32_16x16x32_bf16 v[98:101], v[172:175], v[188:191], v[98:101]
	v_mfma_f32_16x16x32_bf16 v[102:105], v[164:167], v[188:191], v[102:105]
	v_mfma_f32_16x16x32_bf16 v[86:89], v[164:167], v[196:199], v[86:89]
	v_mfma_f32_16x16x32_bf16 v[82:85], v[172:175], v[196:199], v[82:85]
	v_mfma_f32_16x16x32_bf16 v[66:69], v[172:175], v[224:227], v[66:69]
	v_mfma_f32_16x16x32_bf16 v[70:73], v[164:167], v[224:227], v[70:73]
	v_mfma_f32_16x16x32_bf16 v[118:121], v[168:171], v[184:187], v[118:121]
	v_mfma_f32_16x16x32_bf16 v[114:117], v[176:179], v[184:187], v[114:117]
	v_mfma_f32_16x16x32_bf16 v[98:101], v[176:179], v[192:195], v[98:101]
	v_mfma_f32_16x16x32_bf16 v[102:105], v[168:171], v[192:195], v[102:105]
	v_mfma_f32_16x16x32_bf16 v[86:89], v[168:171], v[220:223], v[86:89]
	v_mfma_f32_16x16x32_bf16 v[82:85], v[176:179], v[220:223], v[82:85]
	v_mfma_f32_16x16x32_bf16 v[66:69], v[176:179], v[228:231], v[66:69]
	v_mfma_f32_16x16x32_bf16 v[70:73], v[168:171], v[228:231], v[70:73]
	s_setprio 0
	s_barrier
	s_add_i32 s10, s10, s63
	v_lshl_add_u64 v[200:201], s[24:25], 0, v[0:1]
	s_mov_b32 m0, s10
	ds_read_b128 v[180:183], v218 offset:16384
	ds_read_b128 v[184:187], v218 offset:17408
	ds_read_b128 v[188:191], v218 offset:18432
	ds_read_b128 v[192:195], v218 offset:19456
	ds_read_b128 v[196:199], v218 offset:20480
	ds_read_b128 v[220:223], v218 offset:21504
	ds_read_b128 v[224:227], v218 offset:22528
	ds_read_b128 v[228:231], v218 offset:23552
	global_load_lds_dwordx4 v[200:201], off
	s_add_i32 m0, s10, 0x2000
	s_add_u32 s10, s24, 0x200000
	v_lshl_add_u64 v[232:233], s[24:25], 0, v[142:143]
	s_addc_u32 s11, s25, 0
	s_add_i32 s12, s12, s63
	global_load_lds_dwordx4 v[232:233], off
	v_lshl_add_u64 v[234:235], s[10:11], 0, v[0:1]
	s_mov_b32 m0, s12
	v_lshl_add_u64 v[236:237], s[26:27], 0, v[142:143]
	global_load_lds_dwordx4 v[234:235], off
	v_lshl_add_u64 v[234:235], s[10:11], 0, v[142:143]
	s_add_i32 m0, s12, 0x2000
	s_nop 0
	global_load_lds_dwordx4 v[234:235], off
	v_lshl_add_u64 v[234:235], s[26:27], 0, v[0:1]
	s_mov_b32 m0, s64
	s_nop 0
	global_load_lds_dwordx4 v[234:235], off
	s_mov_b32 m0, s65
	s_nop 0
	global_load_lds_dwordx4 v[236:237], off
	s_waitcnt vmcnt(8)
	s_waitcnt lgkmcnt(0)
	s_barrier
; #define PG8_STAGE(bufoff, gbase, voff) do { _Pragma("unroll") for (int _i = 0; _i < 2; ++_i) \
;         __builtin_amdgcn_global_load_lds((const unsigned*)((const char*)(gbase) + (voff)[_i]), (PG8_LAS unsigned*)(lds + (bufoff) + ldsw + _i * 8192), 16, 0, 0); } while (0)
; #define PG8_LDA(dst, b, h) do { _Pragma("unroll") for (int m = 0; m < 4; ++m) _Pragma("unroll") for (int k = 0; k < 2; ++k) dst[m][k] = *(const PG8_LAS bf16x8*)(lds + PG8_SA(b, h) + aoff + m * 2048 + k * 1024); } while (0)
; #define PG8_LDB(dst, b, h) do { _Pragma("unroll") for (int n = 0; n < 2; ++n) _Pragma("unroll") for (int k = 0; k < 2; ++k) dst[n][k] = *(const PG8_LAS bf16x8*)(lds + PG8_SB(b, h) + boff + n * 2048 + k * 1024); } while (0)
; #define PG8_MMA(ai, bj, At, Bt) do { __builtin_amdgcn_s_setprio(1); _Pragma("unroll") for (int m = 0; m < 4; ++m) _Pragma("unroll") for (int n = 0; n < 2; ++n) _Pragma("unroll") for (int k = 0; k < 2; ++k) \
;         acc[ai][bj][m][n] = __builtin_amdgcn_mfma_f32_16x16x32_bf16(Bt[n][k], At[m][k], acc[ai][bj][m][n], 0, 0, 0); __builtin_amdgcn_s_setprio(0); } while (0)
; #define PG8_WAIT_V(n) asm volatile("s_waitcnt vmcnt(" #n ")" ::: "memory")
; #define PG8_WAIT_L(n) asm volatile("s_waitcnt lgkmcnt(" #n ")" ::: "memory")
; #define PG8_BAR __builtin_amdgcn_s_barrier()
; #define PG8_SCHED __builtin_amdgcn_sched_barrier(0)
; template <class Epi, class Sched, bool ALIGN_EPI = false, bool SP2 = false>
; __device__ __forceinline__ void gemm_phase(PG8_LAS unsigned char* lds, const Gemm g, const Sched& S, const Epi& E) {
;     ...
;             PG8_WAIT_V(8); PG8_WAIT_L(0); PG8_BAR; PG8_MMA(1, 0, At, B0); PG8_MMA(1, 1, At, B1); PG8_BAR; PG8_SCHED;
;             PG8_LDB(B0, 1, 0); PG8_LDB(B1, 1, 1); PG8_SCHED; PG8_LDA(At, 1, 0); PG8_STAGE(PG8_SA(0, 1), a2 + hstep, voffA);
;             PG8_WAIT_V(8); PG8_WAIT_L(0); PG8_BAR; PG8_MMA(0, 0, At, B0); PG8_MMA(0, 1, At, B1); PG8_BAR; PG8_SCHED;
	s_setprio 1
	s_waitcnt lgkmcnt(0)
	v_mfma_f32_16x16x32_bf16 v[62:65], v[148:151], v[180:183], v[62:65]
	v_mfma_f32_16x16x32_bf16 v[58:61], v[156:159], v[180:183], v[58:61]
	v_mfma_f32_16x16x32_bf16 v[42:45], v[156:159], v[188:191], v[42:45]
	v_mfma_f32_16x16x32_bf16 v[46:49], v[148:151], v[188:191], v[46:49]
	v_mfma_f32_16x16x32_bf16 v[30:33], v[148:151], v[196:199], v[30:33]
	v_mfma_f32_16x16x32_bf16 v[26:29], v[156:159], v[196:199], v[26:29]
	v_mfma_f32_16x16x32_bf16 v[10:13], v[156:159], v[224:227], v[10:13]
	v_mfma_f32_16x16x32_bf16 v[14:17], v[148:151], v[224:227], v[14:17]
	v_mfma_f32_16x16x32_bf16 v[62:65], v[152:155], v[184:187], v[62:65]
	v_mfma_f32_16x16x32_bf16 v[58:61], v[160:163], v[184:187], v[58:61]
	v_mfma_f32_16x16x32_bf16 v[42:45], v[160:163], v[192:195], v[42:45]
	v_mfma_f32_16x16x32_bf16 v[46:49], v[152:155], v[192:195], v[46:49]
	v_mfma_f32_16x16x32_bf16 v[30:33], v[152:155], v[220:223], v[30:33]
	v_mfma_f32_16x16x32_bf16 v[26:29], v[160:163], v[220:223], v[26:29]
	v_mfma_f32_16x16x32_bf16 v[10:13], v[160:163], v[228:231], v[10:13]
	v_mfma_f32_16x16x32_bf16 v[14:17], v[152:155], v[228:231], v[14:17]
	s_setprio 0
	s_setprio 1
	v_mfma_f32_16x16x32_bf16 v[54:57], v[164:167], v[180:183], v[54:57]
	v_mfma_f32_16x16x32_bf16 v[50:53], v[172:175], v[180:183], v[50:53]
	v_mfma_f32_16x16x32_bf16 v[34:37], v[172:175], v[188:191], v[34:37]
	v_mfma_f32_16x16x32_bf16 v[38:41], v[164:167], v[188:191], v[38:41]
	v_mfma_f32_16x16x32_bf16 v[22:25], v[164:167], v[196:199], v[22:25]
	v_mfma_f32_16x16x32_bf16 v[18:21], v[172:175], v[196:199], v[18:21]
	v_mfma_f32_16x16x32_bf16 v[2:5], v[172:175], v[224:227], v[2:5]
	v_mfma_f32_16x16x32_bf16 v[6:9], v[164:167], v[224:227], v[6:9]
	v_mfma_f32_16x16x32_bf16 v[54:57], v[168:171], v[184:187], v[54:57]
	v_mfma_f32_16x16x32_bf16 v[50:53], v[176:179], v[184:187], v[50:53]
	v_mfma_f32_16x16x32_bf16 v[34:37], v[176:179], v[192:195], v[34:37]
	v_mfma_f32_16x16x32_bf16 v[38:41], v[168:171], v[192:195], v[38:41]
	v_mfma_f32_16x16x32_bf16 v[22:25], v[168:171], v[220:223], v[22:25]
	v_mfma_f32_16x16x32_bf16 v[18:21], v[176:179], v[220:223], v[18:21]
	v_mfma_f32_16x16x32_bf16 v[2:5], v[176:179], v[228:231], v[2:5]
	v_mfma_f32_16x16x32_bf16 v[6:9], v[168:171], v[228:231], v[6:9]
	s_setprio 0
	s_barrier
	s_add_i32 s12, 0, 0x18000
	s_add_i32 s13, 0, 0x1c000
	v_add_u32_e32 v160, s12, v216
	v_add_u32_e32 v176, s13, v216
	ds_read_b128 v[148:151], v160
	ds_read_b128 v[152:155], v160 offset:1024
	ds_read_b128 v[156:159], v160 offset:2048
	ds_read_b128 v[160:163], v160 offset:3072
	ds_read_b128 v[164:167], v176
	ds_read_b128 v[168:171], v176 offset:1024
	ds_read_b128 v[172:175], v176 offset:2048
	ds_read_b128 v[176:179], v176 offset:3072
	s_add_u32 s10, s26, 0x200000
	s_addc_u32 s11, s27, 0
	s_mov_b32 m0, s66
	v_lshl_add_u64 v[238:239], s[10:11], 0, v[0:1]
	ds_read_b128 v[180:183], v218 offset:32768
	ds_read_b128 v[184:187], v218 offset:33792
	ds_read_b128 v[188:191], v218 offset:34816
	ds_read_b128 v[192:195], v218 offset:35840
	ds_read_b128 v[196:199], v218 offset:36864
	ds_read_b128 v[220:223], v218 offset:37888
	ds_read_b128 v[224:227], v218 offset:38912
	ds_read_b128 v[228:231], v218 offset:39936
	global_load_lds_dwordx4 v[238:239], off
	v_lshl_add_u64 v[238:239], s[10:11], 0, v[142:143]
	s_mov_b32 m0, s67
	s_nop 0
	global_load_lds_dwordx4 v[238:239], off
	s_waitcnt vmcnt(8)
	s_waitcnt lgkmcnt(0)
	s_barrier
	s_setprio 1
	s_waitcnt lgkmcnt(0)
	v_mfma_f32_16x16x32_bf16 v[126:129], v[148:151], v[180:183], v[126:129]
	v_mfma_f32_16x16x32_bf16 v[122:125], v[156:159], v[180:183], v[122:125]
	v_mfma_f32_16x16x32_bf16 v[106:109], v[156:159], v[188:191], v[106:109]
	v_mfma_f32_16x16x32_bf16 v[110:113], v[148:151], v[188:191], v[110:113]
	v_mfma_f32_16x16x32_bf16 v[94:97], v[148:151], v[196:199], v[94:97]
	v_mfma_f32_16x16x32_bf16 v[90:93], v[156:159], v[196:199], v[90:93]
	v_mfma_f32_16x16x32_bf16 v[74:77], v[156:159], v[224:227], v[74:77]
	v_mfma_f32_16x16x32_bf16 v[78:81], v[148:151], v[224:227], v[78:81]
	v_mfma_f32_16x16x32_bf16 v[126:129], v[152:155], v[184:187], v[126:129]
	v_mfma_f32_16x16x32_bf16 v[122:125], v[160:163], v[184:187], v[122:125]
	v_mfma_f32_16x16x32_bf16 v[106:109], v[160:163], v[192:195], v[106:109]
	v_mfma_f32_16x16x32_bf16 v[110:113], v[152:155], v[192:195], v[110:113]
	v_mfma_f32_16x16x32_bf16 v[94:97], v[152:155], v[220:223], v[94:97]
	v_mfma_f32_16x16x32_bf16 v[90:93], v[160:163], v[220:223], v[90:93]
	v_mfma_f32_16x16x32_bf16 v[74:77], v[160:163], v[228:231], v[74:77]
	v_mfma_f32_16x16x32_bf16 v[78:81], v[152:155], v[228:231], v[78:81]
	s_setprio 0
	s_setprio 1
	v_mfma_f32_16x16x32_bf16 v[118:121], v[164:167], v[180:183], v[118:121]
	v_mfma_f32_16x16x32_bf16 v[114:117], v[172:175], v[180:183], v[114:117]
	v_mfma_f32_16x16x32_bf16 v[98:101], v[172:175], v[188:191], v[98:101]
	v_mfma_f32_16x16x32_bf16 v[102:105], v[164:167], v[188:191], v[102:105]
	v_mfma_f32_16x16x32_bf16 v[86:89], v[164:167], v[196:199], v[86:89]
	v_mfma_f32_16x16x32_bf16 v[82:85], v[172:175], v[196:199], v[82:85]
	v_mfma_f32_16x16x32_bf16 v[66:69], v[172:175], v[224:227], v[66:69]
	v_mfma_f32_16x16x32_bf16 v[70:73], v[164:167], v[224:227], v[70:73]
	v_mfma_f32_16x16x32_bf16 v[118:121], v[168:171], v[184:187], v[118:121]
	v_mfma_f32_16x16x32_bf16 v[114:117], v[176:179], v[184:187], v[114:117]
	v_mfma_f32_16x16x32_bf16 v[98:101], v[176:179], v[192:195], v[98:101]
	v_mfma_f32_16x16x32_bf16 v[102:105], v[168:171], v[192:195], v[102:105]
	v_mfma_f32_16x16x32_bf16 v[86:89], v[168:171], v[220:223], v[86:89]
	v_mfma_f32_16x16x32_bf16 v[82:85], v[176:179], v[220:223], v[82:85]
	v_mfma_f32_16x16x32_bf16 v[66:69], v[176:179], v[228:231], v[66:69]
	v_mfma_f32_16x16x32_bf16 v[70:73], v[168:171], v[228:231], v[70:73]
	s_setprio 0
	s_barrier
; #define PG8_STAGE(bufoff, gbase, voff) do { _Pragma("unroll") for (int _i = 0; _i < 2; ++_i) \
;         __builtin_amdgcn_global_load_lds((const unsigned*)((const char*)(gbase) + (voff)[_i]), (PG8_LAS unsigned*)(lds + (bufoff) + ldsw + _i * 8192), 16, 0, 0); } while (0)
; #define PG8_WAIT_V(n) asm volatile("s_waitcnt vmcnt(" #n ")" ::: "memory")
; #define PG8_WAIT_L(n) asm volatile("s_waitcnt lgkmcnt(" #n ")" ::: "memory")
;     __device__ __forceinline__ void operator()(const f32x4 (&acc)[2][2][4][2], const Unit& u, int wr, int wc, int fr, int fq) const {
;         const int row0 = u.pm * BM + wr * 64 + fr; const int col0 = u.pn * BM + wc * 32 + 4 * fq;
; #pragma unroll
;         for (int ai = 0; ai < 2; ++ai) {
;             u32x2 bv[4][2][2];
; #pragma unroll
;             for (int m = 0; m < 4; ++m) { const size_t off = (size_t)(row0 + ai * HALF + m * 16) * ldc + col0;
; #pragma unroll
;                 for (int bj = 0; bj < 2; ++bj)
; #pragma unroll
;                     for (int n = 0; n < 2; ++n) bv[m][bj][n] = *(const u32x2*)(xb + off + bj * HALF + n * 16); }
;             asm volatile("" ::: "memory");
; #pragma unroll
;             for (int m = 0; m < 4; ++m) {
;                 const int row = row0 + ai * HALF + m * 16;
;                 const size_t off = (size_t)row * ldc + col0;
;                 float s = 0.f;
; #pragma unroll
;                 for (int bj = 0; bj < 2; ++bj)
; #pragma unroll
;                     for (int n = 0; n < 2; ++n) {
;                         const size_t c = off + bj * HALF + n * 16;
;                         const u32x2 w0 = bv[m][bj][n];
;                         const f32x4 b = {__uint_as_float(w0.x << 16), __uint_as_float(w0.x & 0xffff0000u), __uint_as_float(w0.y << 16), __uint_as_float(w0.y & 0xffff0000u)};
;                         const f32x4 o = b + acc[ai][bj][m][n];
;                         if (fin) { *(f32x4*)(outf + c) = o; }
; template <class Epi, class Sched, bool ALIGN_EPI = false, bool SP2 = false>
; __device__ __forceinline__ void gemm_phase(PG8_LAS unsigned char* lds, const Gemm g, const Sched& S, const Epi& E) {
;     ...
;             PG8_LDA(At, 1, 1); PG8_STAGE(PG8_SB(1, 0), b3, voffB); PG8_STAGE(PG8_SB(1, 1), b3 + hstep, voffB); PG8_STAGE(PG8_SA(1, 0), a3, voffA);
;             PG8_WAIT_V(8); PG8_WAIT_L(0); PG8_BAR; PG8_MMA(1, 0, At, B0); PG8_MMA(1, 1, At, B1); PG8_BAR; PG8_SCHED;
	s_add_i32 s10, s12, s63
	v_lshl_add_u64 v[200:201], v[200:201], 0, s[30:31]
	s_mov_b32 m0, s10
	ds_read_b128 v[180:183], v218 offset:49152
	ds_read_b128 v[184:187], v218 offset:50176
	ds_read_b128 v[188:191], v218 offset:51200
	ds_read_b128 v[192:195], v218 offset:52224
	ds_read_b128 v[196:199], v218 offset:53248
	ds_read_b128 v[220:223], v218 offset:54272
	ds_read_b128 v[224:227], v218 offset:55296
	ds_read_b128 v[228:231], v218 offset:56320
	global_load_lds_dwordx4 v[200:201], off
	s_add_i32 m0, s10, 0x2000
	s_add_u32 s10, s24, 0x200080
	v_lshl_add_u64 v[200:201], v[232:233], 0, s[30:31]
	s_addc_u32 s11, s25, 0
	s_add_i32 s12, s13, s63
	global_load_lds_dwordx4 v[200:201], off
	v_lshl_add_u64 v[200:201], s[10:11], 0, v[0:1]
	s_mov_b32 m0, s12
	s_nop 0
	global_load_lds_dwordx4 v[200:201], off
	v_lshl_add_u64 v[200:201], s[10:11], 0, v[142:143]
	s_add_i32 m0, s12, 0x2000
	s_nop 0
	global_load_lds_dwordx4 v[200:201], off
	v_lshl_add_u64 v[200:201], v[234:235], 0, s[30:31]
	s_mov_b32 m0, s68
	s_nop 0
	global_load_lds_dwordx4 v[200:201], off
	v_lshl_add_u64 v[200:201], v[236:237], 0, s[30:31]
	s_mov_b32 m0, s69
	s_nop 0
	global_load_lds_dwordx4 v[200:201], off
	s_waitcnt vmcnt(8)
	s_waitcnt lgkmcnt(0)
	s_barrier
	s_setprio 1
	s_waitcnt lgkmcnt(0)
	v_mfma_f32_16x16x32_bf16 v[62:65], v[148:151], v[180:183], v[62:65]
	v_mfma_f32_16x16x32_bf16 v[58:61], v[156:159], v[180:183], v[58:61]
	v_mfma_f32_16x16x32_bf16 v[42:45], v[156:159], v[188:191], v[42:45]
	v_mfma_f32_16x16x32_bf16 v[46:49], v[148:151], v[188:191], v[46:49]
	v_mfma_f32_16x16x32_bf16 v[30:33], v[148:151], v[196:199], v[30:33]
	v_mfma_f32_16x16x32_bf16 v[26:29], v[156:159], v[196:199], v[26:29]
	v_mfma_f32_16x16x32_bf16 v[10:13], v[156:159], v[224:227], v[10:13]
	v_mfma_f32_16x16x32_bf16 v[14:17], v[148:151], v[224:227], v[14:17]
	v_mfma_f32_16x16x32_bf16 v[62:65], v[152:155], v[184:187], v[62:65]
	v_mfma_f32_16x16x32_bf16 v[58:61], v[160:163], v[184:187], v[58:61]
	v_mfma_f32_16x16x32_bf16 v[42:45], v[160:163], v[192:195], v[42:45]
	v_mfma_f32_16x16x32_bf16 v[46:49], v[152:155], v[192:195], v[46:49]
	v_mfma_f32_16x16x32_bf16 v[30:33], v[152:155], v[220:223], v[30:33]
	v_mfma_f32_16x16x32_bf16 v[26:29], v[160:163], v[220:223], v[26:29]
	v_mfma_f32_16x16x32_bf16 v[10:13], v[160:163], v[228:231], v[10:13]
	v_mfma_f32_16x16x32_bf16 v[14:17], v[152:155], v[228:231], v[14:17]
	s_setprio 0
	s_setprio 1
	v_mfma_f32_16x16x32_bf16 v[54:57], v[164:167], v[180:183], v[54:57]
	v_mfma_f32_16x16x32_bf16 v[50:53], v[172:175], v[180:183], v[50:53]
	v_mfma_f32_16x16x32_bf16 v[34:37], v[172:175], v[188:191], v[34:37]
	v_mfma_f32_16x16x32_bf16 v[38:41], v[164:167], v[188:191], v[38:41]
	v_mfma_f32_16x16x32_bf16 v[22:25], v[164:167], v[196:199], v[22:25]
	v_mfma_f32_16x16x32_bf16 v[18:21], v[172:175], v[196:199], v[18:21]
	v_mfma_f32_16x16x32_bf16 v[2:5], v[172:175], v[224:227], v[2:5]
	v_mfma_f32_16x16x32_bf16 v[6:9], v[164:167], v[224:227], v[6:9]
	v_mfma_f32_16x16x32_bf16 v[54:57], v[168:171], v[184:187], v[54:57]
	v_mfma_f32_16x16x32_bf16 v[50:53], v[176:179], v[184:187], v[50:53]
	v_mfma_f32_16x16x32_bf16 v[34:37], v[176:179], v[192:195], v[34:37]
	v_mfma_f32_16x16x32_bf16 v[38:41], v[168:171], v[192:195], v[38:41]
	v_mfma_f32_16x16x32_bf16 v[22:25], v[168:171], v[220:223], v[22:25]
	v_mfma_f32_16x16x32_bf16 v[18:21], v[176:179], v[220:223], v[18:21]
	v_mfma_f32_16x16x32_bf16 v[2:5], v[176:179], v[228:231], v[2:5]
	v_mfma_f32_16x16x32_bf16 v[6:9], v[168:171], v[228:231], v[6:9]
	s_setprio 0
	s_barrier
	s_add_i32 s22, s22, 2
	s_add_u32 s14, s14, 0x100
	s_addc_u32 s15, s15, 0
	s_cmpk_gt_u32 s22, 0x7d
	s_mov_b64 s[16:17], s[18:19]
	s_cbranch_scc0 .LBB0_758
	v_lshl_add_u32 v152, s4, 8, v215
	v_lshl_or_b32 v148, s2, 8, v217
	v_ashrrev_i32_e32 v149, 31, v148
	v_ashrrev_i32_e32 v153, 31, v152
	v_or_b32_e32 v176, 16, v152
	v_lshl_add_u64 v[150:151], v[148:149], 1, s[50:51]
	v_lshlrev_b64 v[154:155], 12, v[152:153]
	v_ashrrev_i32_e32 v177, 31, v176
	v_or_b32_e32 v164, 32, v152
	v_lshl_add_u64 v[198:199], v[150:151], 0, v[154:155]
	v_lshlrev_b64 v[154:155], 12, v[176:177]
	v_ashrrev_i32_e32 v165, 31, v164
	v_lshl_add_u64 v[186:187], v[150:151], 0, v[154:155]
	v_lshlrev_b64 v[154:155], 12, v[164:165]
	v_lshl_add_u64 v[174:175], v[150:151], 0, v[154:155]
	v_or_b32_e32 v154, 48, v152
	v_ashrrev_i32_e32 v155, 31, v154
	v_lshlrev_b64 v[156:157], 12, v[154:155]
	v_lshl_add_u64 v[162:163], v[150:151], 0, v[156:157]
	global_load_dwordx2 v[192:193], v[198:199], off
	global_load_dwordx2 v[196:197], v[198:199], off offset:32
	global_load_dwordx2 v[194:195], v[198:199], off offset:256
	global_load_dwordx2 v[190:191], v[198:199], off offset:288
	global_load_dwordx2 v[188:189], v[186:187], off
	global_load_dwordx2 v[184:185], v[186:187], off offset:32
	global_load_dwordx2 v[182:183], v[186:187], off offset:256
	global_load_dwordx2 v[180:181], v[186:187], off offset:288
	global_load_dwordx2 v[178:179], v[174:175], off
	global_load_dwordx2 v[172:173], v[174:175], off offset:32
	global_load_dwordx2 v[170:171], v[174:175], off offset:256
	global_load_dwordx2 v[168:169], v[174:175], off offset:288
	global_load_dwordx2 v[166:167], v[162:163], off
	global_load_dwordx2 v[160:161], v[162:163], off offset:32
	global_load_dwordx2 v[158:159], v[162:163], off offset:256
	global_load_dwordx2 v[156:157], v[162:163], off offset:288
	v_readlane_b32 s4, v244, 52
	v_readlane_b32 s5, v244, 53
	s_mov_b64 s[16:17], -1
	s_andn2_b64 vcc, exec, s[4:5]
	v_cndmask_b32_e64 v200, 0, 1, s[4:5]
	v_cmp_ne_u32_e64 s[44:45], 1, v200
	v_lshlrev_b64 v[200:201], 11, v[152:153]
	v_lshl_add_u64 v[200:201], v[200:201], 0, v[148:149]
	s_waitcnt vmcnt(0)
	v_lshlrev_b32_e32 v220, 16, v192
	v_and_b32_e32 v221, 0xffff0000, v192
	v_lshlrev_b32_e32 v192, 16, v193
	v_and_b32_e32 v193, 0xffff0000, v193
	v_pk_add_f32 v[128:129], v[128:129], v[192:193]
	v_pk_add_f32 v[126:127], v[126:127], v[220:221]
	v_lshl_add_u64 v[192:193], v[200:201], 2, s[48:49]
	s_cbranch_vccnz .LBB0_761
	s_mov_b64 s[16:17], 0
	global_store_dwordx4 v[192:193], v[126:129], off
